# back-edge rotation of the 6 GEMM K-loops (loop-carried SALU moved into last load segment, next iteration's first ds_reads right after loop-back barrier) on v195
# baseline (speedup 1.0000x reference)
.Lmy_rot2_head:
	s_add_u32 s42, s26, 0xfff80080
	s_addc_u32 s43, s27, -1
	s_cmp_eq_u32 s77, 28
	s_cselect_b32 s45, s17, s43
	s_cselect_b32 s44, s76, s42
	s_cselect_b32 s43, s15, s31
	s_cselect_b32 s42, s33, s30
	v_lshl_add_u64 v[220:221], s[26:27], 0, v[140:141]
	s_add_i32 m0, s57, 0xc000
	ds_read_b128 v[188:191], v154
	ds_read_b128 v[192:195], v154 offset:1024
	ds_read_b128 v[196:199], v154 offset:2048
	ds_read_b128 v[200:203], v154 offset:3072
	ds_read_b128 v[204:207], v154 offset:4096
	ds_read_b128 v[208:211], v154 offset:5120
	ds_read_b128 v[212:215], v154 offset:6144
	ds_read_b128 v[216:219], v154 offset:7168
	global_load_lds_dwordx4 v[220:221], off
	v_lshl_add_u64 v[220:221], s[26:27], 0, v[142:143]
	s_add_i32 m0, s57, 0xe000
	s_nop 0
	global_load_lds_dwordx4 v[220:221], off
	s_waitcnt vmcnt(8)
	s_waitcnt lgkmcnt(0)
	s_barrier
	s_setprio 1
	s_waitcnt lgkmcnt(0)
	v_mfma_f32_16x16x32_bf16 v[126:129], v[156:159], v[188:191], v[126:129]
	v_mfma_f32_16x16x32_bf16 v[122:125], v[164:167], v[188:191], v[122:125]
	v_mfma_f32_16x16x32_bf16 v[110:113], v[156:159], v[196:199], v[110:113]
	v_mfma_f32_16x16x32_bf16 v[106:109], v[164:167], v[196:199], v[106:109]
	v_mfma_f32_16x16x32_bf16 v[94:97], v[156:159], v[204:207], v[94:97]
	v_mfma_f32_16x16x32_bf16 v[90:93], v[164:167], v[204:207], v[90:93]
	v_mfma_f32_16x16x32_bf16 v[78:81], v[156:159], v[212:215], v[78:81]
	v_mfma_f32_16x16x32_bf16 v[74:77], v[164:167], v[212:215], v[74:77]
	v_mfma_f32_16x16x32_bf16 v[126:129], v[160:163], v[192:195], v[126:129]
	v_mfma_f32_16x16x32_bf16 v[122:125], v[168:171], v[192:195], v[122:125]
	v_mfma_f32_16x16x32_bf16 v[110:113], v[160:163], v[200:203], v[110:113]
	v_mfma_f32_16x16x32_bf16 v[106:109], v[168:171], v[200:203], v[106:109]
	v_mfma_f32_16x16x32_bf16 v[94:97], v[160:163], v[208:211], v[94:97]
	v_mfma_f32_16x16x32_bf16 v[90:93], v[168:171], v[208:211], v[90:93]
	v_mfma_f32_16x16x32_bf16 v[78:81], v[160:163], v[216:219], v[78:81]
	v_mfma_f32_16x16x32_bf16 v[74:77], v[168:171], v[216:219], v[74:77]
	s_setprio 0
	s_setprio 1
	v_mfma_f32_16x16x32_bf16 v[118:121], v[172:175], v[188:191], v[118:121]
	v_mfma_f32_16x16x32_bf16 v[114:117], v[180:183], v[188:191], v[114:117]
	v_mfma_f32_16x16x32_bf16 v[102:105], v[172:175], v[196:199], v[102:105]
	v_mfma_f32_16x16x32_bf16 v[98:101], v[180:183], v[196:199], v[98:101]
	v_mfma_f32_16x16x32_bf16 v[86:89], v[172:175], v[204:207], v[86:89]
	v_mfma_f32_16x16x32_bf16 v[82:85], v[180:183], v[204:207], v[82:85]
	v_mfma_f32_16x16x32_bf16 v[70:73], v[172:175], v[212:215], v[70:73]
	v_mfma_f32_16x16x32_bf16 v[66:69], v[180:183], v[212:215], v[66:69]
	v_mfma_f32_16x16x32_bf16 v[118:121], v[176:179], v[192:195], v[118:121]
	v_mfma_f32_16x16x32_bf16 v[114:117], v[184:187], v[192:195], v[114:117]
	v_mfma_f32_16x16x32_bf16 v[102:105], v[176:179], v[200:203], v[102:105]
	v_mfma_f32_16x16x32_bf16 v[98:101], v[184:187], v[200:203], v[98:101]
	v_mfma_f32_16x16x32_bf16 v[86:89], v[176:179], v[208:211], v[86:89]
	v_mfma_f32_16x16x32_bf16 v[82:85], v[184:187], v[208:211], v[82:85]
	v_mfma_f32_16x16x32_bf16 v[70:73], v[176:179], v[216:219], v[70:73]
	v_mfma_f32_16x16x32_bf16 v[66:69], v[184:187], v[216:219], v[66:69]
	s_setprio 0
	s_barrier
	s_add_i32 s78, s73, s34
	v_lshl_add_u64 v[220:221], s[42:43], 0, v[132:133]
	s_mov_b32 m0, s78
	ds_read_b128 v[188:191], v154 offset:16384
	ds_read_b128 v[192:195], v154 offset:17408
	ds_read_b128 v[196:199], v154 offset:18432
	ds_read_b128 v[200:203], v154 offset:19456
	ds_read_b128 v[204:207], v154 offset:20480
	ds_read_b128 v[208:211], v154 offset:21504
	ds_read_b128 v[212:215], v154 offset:22528
	ds_read_b128 v[216:219], v154 offset:23552
	global_load_lds_dwordx4 v[220:221], off
	s_add_i32 m0, s78, 0x2000
	s_add_u32 s78, s42, 0x4000
	v_lshl_add_u64 v[220:221], s[42:43], 0, v[136:137]
	s_addc_u32 s79, s43, 0
	s_add_i32 s82, s74, s34
	global_load_lds_dwordx4 v[220:221], off
	v_lshl_add_u64 v[220:221], s[78:79], 0, v[132:133]
	s_mov_b32 m0, s82
	v_lshl_add_u64 v[222:223], s[44:45], 0, v[134:135]
	global_load_lds_dwordx4 v[220:221], off
	v_lshl_add_u64 v[220:221], s[78:79], 0, v[136:137]
	s_add_i32 m0, s82, 0x2000
	s_nop 0
	global_load_lds_dwordx4 v[220:221], off
	v_lshl_add_u64 v[220:221], s[44:45], 0, v[130:131]
	s_mov_b32 m0, s57
	s_nop 0
	global_load_lds_dwordx4 v[220:221], off
	s_mov_b32 m0, s58
	s_nop 0
	global_load_lds_dwordx4 v[222:223], off
	s_waitcnt vmcnt(8)
	s_waitcnt lgkmcnt(0)
	s_barrier
	s_setprio 1
	s_waitcnt lgkmcnt(0)
	v_mfma_f32_16x16x32_bf16 v[62:65], v[156:159], v[188:191], v[62:65]
	v_mfma_f32_16x16x32_bf16 v[58:61], v[164:167], v[188:191], v[58:61]
	v_mfma_f32_16x16x32_bf16 v[46:49], v[156:159], v[196:199], v[46:49]
	v_mfma_f32_16x16x32_bf16 v[42:45], v[164:167], v[196:199], v[42:45]
	v_mfma_f32_16x16x32_bf16 v[30:33], v[156:159], v[204:207], v[30:33]
	v_mfma_f32_16x16x32_bf16 v[26:29], v[164:167], v[204:207], v[26:29]
	v_mfma_f32_16x16x32_bf16 v[14:17], v[156:159], v[212:215], v[14:17]
	v_mfma_f32_16x16x32_bf16 v[10:13], v[164:167], v[212:215], v[10:13]
	v_mfma_f32_16x16x32_bf16 v[62:65], v[160:163], v[192:195], v[62:65]
	v_mfma_f32_16x16x32_bf16 v[58:61], v[168:171], v[192:195], v[58:61]
	v_mfma_f32_16x16x32_bf16 v[46:49], v[160:163], v[200:203], v[46:49]
	v_mfma_f32_16x16x32_bf16 v[42:45], v[168:171], v[200:203], v[42:45]
	v_mfma_f32_16x16x32_bf16 v[30:33], v[160:163], v[208:211], v[30:33]
	v_mfma_f32_16x16x32_bf16 v[26:29], v[168:171], v[208:211], v[26:29]
	v_mfma_f32_16x16x32_bf16 v[14:17], v[160:163], v[216:219], v[14:17]
	v_mfma_f32_16x16x32_bf16 v[10:13], v[168:171], v[216:219], v[10:13]
	s_setprio 0
	s_setprio 1
	v_mfma_f32_16x16x32_bf16 v[54:57], v[172:175], v[188:191], v[54:57]
	v_mfma_f32_16x16x32_bf16 v[50:53], v[180:183], v[188:191], v[50:53]
	v_mfma_f32_16x16x32_bf16 v[38:41], v[172:175], v[196:199], v[38:41]
	v_mfma_f32_16x16x32_bf16 v[34:37], v[180:183], v[196:199], v[34:37]
	v_mfma_f32_16x16x32_bf16 v[22:25], v[172:175], v[204:207], v[22:25]
	v_mfma_f32_16x16x32_bf16 v[18:21], v[180:183], v[204:207], v[18:21]
	v_mfma_f32_16x16x32_bf16 v[6:9], v[172:175], v[212:215], v[6:9]
	v_mfma_f32_16x16x32_bf16 v[2:5], v[180:183], v[212:215], v[2:5]
	v_mfma_f32_16x16x32_bf16 v[54:57], v[176:179], v[192:195], v[54:57]
	v_mfma_f32_16x16x32_bf16 v[50:53], v[184:187], v[192:195], v[50:53]
	v_mfma_f32_16x16x32_bf16 v[38:41], v[176:179], v[200:203], v[38:41]
	v_mfma_f32_16x16x32_bf16 v[34:37], v[184:187], v[200:203], v[34:37]
	v_mfma_f32_16x16x32_bf16 v[22:25], v[176:179], v[208:211], v[22:25]
	v_mfma_f32_16x16x32_bf16 v[18:21], v[184:187], v[208:211], v[18:21]
	v_mfma_f32_16x16x32_bf16 v[6:9], v[176:179], v[216:219], v[6:9]
	v_mfma_f32_16x16x32_bf16 v[2:5], v[184:187], v[216:219], v[2:5]
	s_setprio 0
	s_barrier
	s_add_i32 s78, 0, 0x18000
	v_add_u32_e32 v138, s78, v151
	s_add_i32 s79, 0, 0x1c000
	ds_read_b128 v[156:159], v138
	ds_read_b128 v[160:163], v138 offset:1024
	ds_read_b128 v[164:167], v138 offset:2048
	ds_read_b128 v[168:171], v138 offset:3072
	v_add_u32_e32 v138, s79, v151
	ds_read_b128 v[172:175], v138
	ds_read_b128 v[176:179], v138 offset:1024
	ds_read_b128 v[180:183], v138 offset:2048
	ds_read_b128 v[184:187], v138 offset:3072
	s_add_u32 s44, s44, 0x80000
	s_addc_u32 s45, s45, 0
	s_mov_b32 m0, s59
	v_lshl_add_u64 v[224:225], s[44:45], 0, v[130:131]
	ds_read_b128 v[188:191], v154 offset:32768
	ds_read_b128 v[192:195], v154 offset:33792
	ds_read_b128 v[196:199], v154 offset:34816
	ds_read_b128 v[200:203], v154 offset:35840
	ds_read_b128 v[204:207], v154 offset:36864
	ds_read_b128 v[208:211], v154 offset:37888
	ds_read_b128 v[212:215], v154 offset:38912
	ds_read_b128 v[216:219], v154 offset:39936
	global_load_lds_dwordx4 v[224:225], off
	v_lshl_add_u64 v[224:225], s[44:45], 0, v[134:135]
	s_mov_b32 m0, s60
	s_nop 0
	global_load_lds_dwordx4 v[224:225], off
	s_waitcnt vmcnt(8)
	s_waitcnt lgkmcnt(0)
	s_barrier
	s_setprio 1
	s_waitcnt lgkmcnt(0)
	v_mfma_f32_16x16x32_bf16 v[126:129], v[156:159], v[188:191], v[126:129]
	v_mfma_f32_16x16x32_bf16 v[122:125], v[164:167], v[188:191], v[122:125]
	v_mfma_f32_16x16x32_bf16 v[110:113], v[156:159], v[196:199], v[110:113]
	v_mfma_f32_16x16x32_bf16 v[106:109], v[164:167], v[196:199], v[106:109]
	v_mfma_f32_16x16x32_bf16 v[94:97], v[156:159], v[204:207], v[94:97]
	v_mfma_f32_16x16x32_bf16 v[90:93], v[164:167], v[204:207], v[90:93]
	v_mfma_f32_16x16x32_bf16 v[78:81], v[156:159], v[212:215], v[78:81]
	v_mfma_f32_16x16x32_bf16 v[74:77], v[164:167], v[212:215], v[74:77]
	v_mfma_f32_16x16x32_bf16 v[126:129], v[160:163], v[192:195], v[126:129]
	v_mfma_f32_16x16x32_bf16 v[122:125], v[168:171], v[192:195], v[122:125]
	v_mfma_f32_16x16x32_bf16 v[110:113], v[160:163], v[200:203], v[110:113]
	v_mfma_f32_16x16x32_bf16 v[106:109], v[168:171], v[200:203], v[106:109]
	v_mfma_f32_16x16x32_bf16 v[94:97], v[160:163], v[208:211], v[94:97]
	v_mfma_f32_16x16x32_bf16 v[90:93], v[168:171], v[208:211], v[90:93]
	v_mfma_f32_16x16x32_bf16 v[78:81], v[160:163], v[216:219], v[78:81]
	v_mfma_f32_16x16x32_bf16 v[74:77], v[168:171], v[216:219], v[74:77]
	s_setprio 0
	s_setprio 1
	v_mfma_f32_16x16x32_bf16 v[118:121], v[172:175], v[188:191], v[118:121]
	v_mfma_f32_16x16x32_bf16 v[114:117], v[180:183], v[188:191], v[114:117]
	v_mfma_f32_16x16x32_bf16 v[102:105], v[172:175], v[196:199], v[102:105]
	v_mfma_f32_16x16x32_bf16 v[98:101], v[180:183], v[196:199], v[98:101]
	v_mfma_f32_16x16x32_bf16 v[86:89], v[172:175], v[204:207], v[86:89]
	v_mfma_f32_16x16x32_bf16 v[82:85], v[180:183], v[204:207], v[82:85]
	v_mfma_f32_16x16x32_bf16 v[70:73], v[172:175], v[212:215], v[70:73]
	v_mfma_f32_16x16x32_bf16 v[66:69], v[180:183], v[212:215], v[66:69]
	v_mfma_f32_16x16x32_bf16 v[118:121], v[176:179], v[192:195], v[118:121]
	v_mfma_f32_16x16x32_bf16 v[114:117], v[184:187], v[192:195], v[114:117]
	v_mfma_f32_16x16x32_bf16 v[102:105], v[176:179], v[200:203], v[102:105]
	v_mfma_f32_16x16x32_bf16 v[98:101], v[184:187], v[200:203], v[98:101]
	v_mfma_f32_16x16x32_bf16 v[86:89], v[176:179], v[208:211], v[86:89]
	v_mfma_f32_16x16x32_bf16 v[82:85], v[184:187], v[208:211], v[82:85]
	v_mfma_f32_16x16x32_bf16 v[70:73], v[176:179], v[216:219], v[70:73]
	v_mfma_f32_16x16x32_bf16 v[66:69], v[184:187], v[216:219], v[66:69]
	s_setprio 0
	s_barrier
	s_add_u32 s44, s42, 0x8000
	s_addc_u32 s45, s43, 0
	s_add_i32 s78, s78, s34
	v_lshl_add_u64 v[224:225], s[44:45], 0, v[132:133]
	s_mov_b32 m0, s78
	ds_read_b128 v[188:191], v154 offset:49152
	ds_read_b128 v[192:195], v154 offset:50176
	ds_read_b128 v[196:199], v154 offset:51200
	ds_read_b128 v[200:203], v154 offset:52224
	ds_read_b128 v[204:207], v154 offset:53248
	ds_read_b128 v[208:211], v154 offset:54272
	ds_read_b128 v[212:215], v154 offset:55296
	ds_read_b128 v[216:219], v154 offset:56320
	global_load_lds_dwordx4 v[224:225], off
	s_add_i32 m0, s78, 0x2000
	s_add_u32 s42, s42, 0xc000
	v_lshl_add_u64 v[224:225], s[44:45], 0, v[136:137]
	s_addc_u32 s43, s43, 0
	s_add_i32 s44, s79, s34
	global_load_lds_dwordx4 v[224:225], off
	v_lshl_add_u64 v[224:225], s[42:43], 0, v[132:133]
	s_mov_b32 m0, s44
	v_lshl_add_u64 v[220:221], v[220:221], 0, s[10:11]
	global_load_lds_dwordx4 v[224:225], off
	v_lshl_add_u64 v[224:225], s[42:43], 0, v[136:137]
	s_add_i32 m0, s44, 0x2000
	s_nop 0
	global_load_lds_dwordx4 v[224:225], off
	s_mov_b32 m0, s69
	s_nop 0
	global_load_lds_dwordx4 v[220:221], off
	v_lshl_add_u64 v[220:221], v[222:223], 0, s[10:11]
	s_mov_b32 m0, s71
	s_nop 0
	global_load_lds_dwordx4 v[220:221], off
	s_add_i32 s77, s77, 2
	s_add_u32 s30, s30, 0x10000
	s_addc_u32 s31, s31, 0
	s_add_u32 s26, s26, 0x100
	s_addc_u32 s27, s27, 0
	s_cmp_gt_u32 s77, 29
	s_waitcnt vmcnt(8)
	s_waitcnt lgkmcnt(0)
	s_barrier
	s_setprio 1
	s_waitcnt lgkmcnt(0)
	v_mfma_f32_16x16x32_bf16 v[62:65], v[156:159], v[188:191], v[62:65]
	v_mfma_f32_16x16x32_bf16 v[58:61], v[164:167], v[188:191], v[58:61]
	v_mfma_f32_16x16x32_bf16 v[46:49], v[156:159], v[196:199], v[46:49]
	v_mfma_f32_16x16x32_bf16 v[42:45], v[164:167], v[196:199], v[42:45]
	v_mfma_f32_16x16x32_bf16 v[30:33], v[156:159], v[204:207], v[30:33]
	v_mfma_f32_16x16x32_bf16 v[26:29], v[164:167], v[204:207], v[26:29]
	v_mfma_f32_16x16x32_bf16 v[14:17], v[156:159], v[212:215], v[14:17]
	v_mfma_f32_16x16x32_bf16 v[10:13], v[164:167], v[212:215], v[10:13]
	v_mfma_f32_16x16x32_bf16 v[62:65], v[160:163], v[192:195], v[62:65]
	v_mfma_f32_16x16x32_bf16 v[58:61], v[168:171], v[192:195], v[58:61]
	v_mfma_f32_16x16x32_bf16 v[46:49], v[160:163], v[200:203], v[46:49]
	v_mfma_f32_16x16x32_bf16 v[42:45], v[168:171], v[200:203], v[42:45]
	v_mfma_f32_16x16x32_bf16 v[30:33], v[160:163], v[208:211], v[30:33]
	v_mfma_f32_16x16x32_bf16 v[26:29], v[168:171], v[208:211], v[26:29]
	v_mfma_f32_16x16x32_bf16 v[14:17], v[160:163], v[216:219], v[14:17]
	v_mfma_f32_16x16x32_bf16 v[10:13], v[168:171], v[216:219], v[10:13]
	s_setprio 0
	s_setprio 1
	v_mfma_f32_16x16x32_bf16 v[54:57], v[172:175], v[188:191], v[54:57]
	v_mfma_f32_16x16x32_bf16 v[50:53], v[180:183], v[188:191], v[50:53]
	v_mfma_f32_16x16x32_bf16 v[38:41], v[172:175], v[196:199], v[38:41]
	v_mfma_f32_16x16x32_bf16 v[34:37], v[180:183], v[196:199], v[34:37]
	v_mfma_f32_16x16x32_bf16 v[22:25], v[172:175], v[204:207], v[22:25]
	v_mfma_f32_16x16x32_bf16 v[18:21], v[180:183], v[204:207], v[18:21]
	v_mfma_f32_16x16x32_bf16 v[6:9], v[172:175], v[212:215], v[6:9]
	v_mfma_f32_16x16x32_bf16 v[2:5], v[180:183], v[212:215], v[2:5]
	v_mfma_f32_16x16x32_bf16 v[54:57], v[176:179], v[192:195], v[54:57]
	v_mfma_f32_16x16x32_bf16 v[50:53], v[184:187], v[192:195], v[50:53]
	v_mfma_f32_16x16x32_bf16 v[38:41], v[176:179], v[200:203], v[38:41]
	v_mfma_f32_16x16x32_bf16 v[34:37], v[184:187], v[200:203], v[34:37]
	v_mfma_f32_16x16x32_bf16 v[22:25], v[176:179], v[208:211], v[22:25]
	v_mfma_f32_16x16x32_bf16 v[18:21], v[184:187], v[208:211], v[18:21]
	v_mfma_f32_16x16x32_bf16 v[6:9], v[176:179], v[216:219], v[6:9]
	v_mfma_f32_16x16x32_bf16 v[2:5], v[184:187], v[216:219], v[2:5]
	s_setprio 0
	s_barrier
	s_cbranch_scc1 .Lmy_rot2_exit
	ds_read_b128 v[156:159], v152
	ds_read_b128 v[160:163], v152 offset:1024
	ds_read_b128 v[164:167], v152 offset:2048
	ds_read_b128 v[168:171], v152 offset:3072
	ds_read_b128 v[172:175], v153
	ds_read_b128 v[176:179], v153 offset:1024
	ds_read_b128 v[180:183], v153 offset:2048
	ds_read_b128 v[184:187], v153 offset:3072
	s_branch .Lmy_rot2_head
.Lmy_rot2_exit:
	s_and_b64 vcc, exec, s[12:13]
	s_cbranch_vccz .LBB0_264
	s_barrier

.Lmy_rot3_head:
	s_add_u32 s20, s18, 0x4000
	s_addc_u32 s21, s19, 0
	s_cmpk_eq_i32 s33, 0x54
	s_cselect_b32 s24, s4, s20
	s_cselect_b32 s25, s5, s21
	s_cselect_b32 s22, s16, s30
	s_cselect_b32 s23, s17, s31
	s_add_u32 s20, s24, 0x8000
	s_addc_u32 s21, s25, 0
	v_lshl_add_u64 v[166:167], s[18:19], 0, v[138:139]
	s_add_i32 m0, s34, 0xc000
	ds_read_b128 v[186:189], v173
	ds_read_b128 v[190:193], v173 offset:1024
	ds_read_b128 v[194:197], v173 offset:2048
	ds_read_b128 v[198:201], v173 offset:3072
	ds_read_b128 v[202:205], v173 offset:4096
	ds_read_b128 v[206:209], v173 offset:5120
	ds_read_b128 v[210:213], v173 offset:6144
	ds_read_b128 v[214:217], v173 offset:7168
	global_load_lds_dwordx4 v[166:167], off
	v_lshl_add_u64 v[166:167], s[18:19], 0, v[140:141]
	s_add_i32 m0, s34, 0xe000
	s_nop 0
	global_load_lds_dwordx4 v[166:167], off
	s_waitcnt vmcnt(8)
	s_waitcnt lgkmcnt(0)
	s_barrier
	s_setprio 1
	s_waitcnt lgkmcnt(0)
	v_mfma_f32_16x16x32_bf16 v[126:129], v[146:149], v[186:189], v[126:129]
	v_mfma_f32_16x16x32_bf16 v[122:125], v[154:157], v[186:189], v[122:125]
	v_mfma_f32_16x16x32_bf16 v[118:121], v[146:149], v[194:197], v[118:121]
	v_mfma_f32_16x16x32_bf16 v[114:117], v[154:157], v[194:197], v[114:117]
	v_mfma_f32_16x16x32_bf16 v[102:105], v[146:149], v[202:205], v[102:105]
	v_mfma_f32_16x16x32_bf16 v[94:97], v[154:157], v[202:205], v[94:97]
	v_mfma_f32_16x16x32_bf16 v[86:89], v[146:149], v[210:213], v[86:89]
	v_mfma_f32_16x16x32_bf16 v[78:81], v[154:157], v[210:213], v[78:81]
	v_mfma_f32_16x16x32_bf16 v[126:129], v[150:153], v[190:193], v[126:129]
	v_mfma_f32_16x16x32_bf16 v[122:125], v[158:161], v[190:193], v[122:125]
	v_mfma_f32_16x16x32_bf16 v[118:121], v[150:153], v[198:201], v[118:121]
	v_mfma_f32_16x16x32_bf16 v[114:117], v[158:161], v[198:201], v[114:117]
	v_mfma_f32_16x16x32_bf16 v[102:105], v[150:153], v[206:209], v[102:105]
	v_mfma_f32_16x16x32_bf16 v[94:97], v[158:161], v[206:209], v[94:97]
	v_mfma_f32_16x16x32_bf16 v[86:89], v[150:153], v[214:217], v[86:89]
	v_mfma_f32_16x16x32_bf16 v[78:81], v[158:161], v[214:217], v[78:81]
	s_setprio 0
	s_setprio 1
	v_mfma_f32_16x16x32_bf16 v[110:113], v[162:165], v[186:189], v[110:113]
	v_mfma_f32_16x16x32_bf16 v[106:109], v[178:181], v[186:189], v[106:109]
	v_mfma_f32_16x16x32_bf16 v[98:101], v[162:165], v[194:197], v[98:101]
	v_mfma_f32_16x16x32_bf16 v[90:93], v[178:181], v[194:197], v[90:93]
	v_mfma_f32_16x16x32_bf16 v[82:85], v[162:165], v[202:205], v[82:85]
	v_mfma_f32_16x16x32_bf16 v[74:77], v[178:181], v[202:205], v[74:77]
	v_mfma_f32_16x16x32_bf16 v[70:73], v[162:165], v[210:213], v[70:73]
	v_mfma_f32_16x16x32_bf16 v[66:69], v[178:181], v[210:213], v[66:69]
	v_mfma_f32_16x16x32_bf16 v[110:113], v[174:177], v[190:193], v[110:113]
	v_mfma_f32_16x16x32_bf16 v[106:109], v[182:185], v[190:193], v[106:109]
	v_mfma_f32_16x16x32_bf16 v[98:101], v[174:177], v[198:201], v[98:101]
	v_mfma_f32_16x16x32_bf16 v[90:93], v[182:185], v[198:201], v[90:93]
	v_mfma_f32_16x16x32_bf16 v[82:85], v[174:177], v[206:209], v[82:85]
	v_mfma_f32_16x16x32_bf16 v[74:77], v[182:185], v[206:209], v[74:77]
	v_mfma_f32_16x16x32_bf16 v[70:73], v[174:177], v[214:217], v[70:73]
	v_mfma_f32_16x16x32_bf16 v[66:69], v[182:185], v[214:217], v[66:69]
	s_setprio 0
	s_barrier
	s_add_i32 s68, s58, s28
	v_lshl_add_u64 v[166:167], s[22:23], 0, v[132:133]
	s_mov_b32 m0, s68
	ds_read_b128 v[186:189], v173 offset:16384
	ds_read_b128 v[190:193], v173 offset:17408
	ds_read_b128 v[194:197], v173 offset:18432
	ds_read_b128 v[198:201], v173 offset:19456
	ds_read_b128 v[202:205], v173 offset:20480
	ds_read_b128 v[206:209], v173 offset:21504
	ds_read_b128 v[210:213], v173 offset:22528
	ds_read_b128 v[214:217], v173 offset:23552
	global_load_lds_dwordx4 v[166:167], off
	s_add_i32 m0, s68, 0x2000
	s_add_u32 s68, s22, 0x4000
	v_lshl_add_u64 v[166:167], s[22:23], 0, v[136:137]
	s_addc_u32 s69, s23, 0
	s_add_i32 s71, s59, s28
	global_load_lds_dwordx4 v[166:167], off
	v_lshl_add_u64 v[166:167], s[68:69], 0, v[132:133]
	s_mov_b32 m0, s71
	s_nop 0
	global_load_lds_dwordx4 v[166:167], off
	v_lshl_add_u64 v[166:167], s[68:69], 0, v[136:137]
	s_add_i32 m0, s71, 0x2000
	s_nop 0
	global_load_lds_dwordx4 v[166:167], off
	v_lshl_add_u64 v[166:167], s[24:25], 0, v[130:131]
	s_mov_b32 m0, s34
	s_nop 0
	global_load_lds_dwordx4 v[166:167], off
	v_lshl_add_u64 v[166:167], s[24:25], 0, v[134:135]
	s_mov_b32 m0, s35
	s_nop 0
	global_load_lds_dwordx4 v[166:167], off
	s_waitcnt vmcnt(8)
	s_waitcnt lgkmcnt(0)
	s_barrier
	s_setprio 1
	s_waitcnt lgkmcnt(0)
	v_mfma_f32_16x16x32_bf16 v[62:65], v[146:149], v[186:189], v[62:65]
	v_mfma_f32_16x16x32_bf16 v[58:61], v[154:157], v[186:189], v[58:61]
	v_mfma_f32_16x16x32_bf16 v[54:57], v[146:149], v[194:197], v[54:57]
	v_mfma_f32_16x16x32_bf16 v[46:49], v[154:157], v[194:197], v[46:49]
	v_mfma_f32_16x16x32_bf16 v[38:41], v[146:149], v[202:205], v[38:41]
	v_mfma_f32_16x16x32_bf16 v[30:33], v[154:157], v[202:205], v[30:33]
	v_mfma_f32_16x16x32_bf16 v[22:25], v[146:149], v[210:213], v[22:25]
	v_mfma_f32_16x16x32_bf16 v[14:17], v[154:157], v[210:213], v[14:17]
	v_mfma_f32_16x16x32_bf16 v[62:65], v[150:153], v[190:193], v[62:65]
	v_mfma_f32_16x16x32_bf16 v[58:61], v[158:161], v[190:193], v[58:61]
	v_mfma_f32_16x16x32_bf16 v[54:57], v[150:153], v[198:201], v[54:57]
	v_mfma_f32_16x16x32_bf16 v[46:49], v[158:161], v[198:201], v[46:49]
	v_mfma_f32_16x16x32_bf16 v[38:41], v[150:153], v[206:209], v[38:41]
	v_mfma_f32_16x16x32_bf16 v[30:33], v[158:161], v[206:209], v[30:33]
	v_mfma_f32_16x16x32_bf16 v[22:25], v[150:153], v[214:217], v[22:25]
	v_mfma_f32_16x16x32_bf16 v[14:17], v[158:161], v[214:217], v[14:17]
	s_setprio 0
	s_setprio 1
	v_mfma_f32_16x16x32_bf16 v[50:53], v[162:165], v[186:189], v[50:53]
	v_mfma_f32_16x16x32_bf16 v[42:45], v[178:181], v[186:189], v[42:45]
	v_mfma_f32_16x16x32_bf16 v[34:37], v[162:165], v[194:197], v[34:37]
	v_mfma_f32_16x16x32_bf16 v[26:29], v[178:181], v[194:197], v[26:29]
	v_mfma_f32_16x16x32_bf16 v[18:21], v[162:165], v[202:205], v[18:21]
	v_mfma_f32_16x16x32_bf16 v[10:13], v[178:181], v[202:205], v[10:13]
	v_mfma_f32_16x16x32_bf16 v[6:9], v[162:165], v[210:213], v[6:9]
	v_mfma_f32_16x16x32_bf16 v[2:5], v[178:181], v[210:213], v[2:5]
	v_mfma_f32_16x16x32_bf16 v[50:53], v[174:177], v[190:193], v[50:53]
	v_mfma_f32_16x16x32_bf16 v[42:45], v[182:185], v[190:193], v[42:45]
	v_mfma_f32_16x16x32_bf16 v[34:37], v[174:177], v[198:201], v[34:37]
	v_mfma_f32_16x16x32_bf16 v[26:29], v[182:185], v[198:201], v[26:29]
	v_mfma_f32_16x16x32_bf16 v[18:21], v[174:177], v[206:209], v[18:21]
	v_mfma_f32_16x16x32_bf16 v[10:13], v[182:185], v[206:209], v[10:13]
	v_mfma_f32_16x16x32_bf16 v[6:9], v[174:177], v[214:217], v[6:9]
	v_mfma_f32_16x16x32_bf16 v[2:5], v[182:185], v[214:217], v[2:5]
	s_setprio 0
	s_barrier
	s_add_i32 s68, 0, 0x18000
	s_add_i32 s69, 0, 0x1c000
	v_add_u32_e32 v158, s68, v169
	v_add_u32_e32 v166, s69, v169
	ds_read_b128 v[146:149], v158
	ds_read_b128 v[150:153], v158 offset:1024
	ds_read_b128 v[154:157], v158 offset:2048
	ds_read_b128 v[158:161], v158 offset:3072
	ds_read_b128 v[162:165], v166
	ds_read_b128 v[174:177], v166 offset:1024
	ds_read_b128 v[178:181], v166 offset:2048
	ds_read_b128 v[182:185], v166 offset:3072
	s_add_u32 s24, s24, 0x4000
	s_addc_u32 s25, s25, 0
	s_mov_b32 m0, s42
	v_lshl_add_u64 v[166:167], s[24:25], 0, v[130:131]
	ds_read_b128 v[186:189], v173 offset:32768
	ds_read_b128 v[190:193], v173 offset:33792
	ds_read_b128 v[194:197], v173 offset:34816
	ds_read_b128 v[198:201], v173 offset:35840
	ds_read_b128 v[202:205], v173 offset:36864
	ds_read_b128 v[206:209], v173 offset:37888
	ds_read_b128 v[210:213], v173 offset:38912
	ds_read_b128 v[214:217], v173 offset:39936
	global_load_lds_dwordx4 v[166:167], off
	v_lshl_add_u64 v[166:167], s[24:25], 0, v[134:135]
	s_mov_b32 m0, s43
	s_nop 0
	global_load_lds_dwordx4 v[166:167], off
	s_waitcnt vmcnt(8)
	s_waitcnt lgkmcnt(0)
	s_barrier
	s_setprio 1
	s_waitcnt lgkmcnt(0)
	v_mfma_f32_16x16x32_bf16 v[126:129], v[146:149], v[186:189], v[126:129]
	v_mfma_f32_16x16x32_bf16 v[122:125], v[154:157], v[186:189], v[122:125]
	v_mfma_f32_16x16x32_bf16 v[118:121], v[146:149], v[194:197], v[118:121]
	v_mfma_f32_16x16x32_bf16 v[114:117], v[154:157], v[194:197], v[114:117]
	v_mfma_f32_16x16x32_bf16 v[102:105], v[146:149], v[202:205], v[102:105]
	v_mfma_f32_16x16x32_bf16 v[94:97], v[154:157], v[202:205], v[94:97]
	v_mfma_f32_16x16x32_bf16 v[86:89], v[146:149], v[210:213], v[86:89]
	v_mfma_f32_16x16x32_bf16 v[78:81], v[154:157], v[210:213], v[78:81]
	v_mfma_f32_16x16x32_bf16 v[126:129], v[150:153], v[190:193], v[126:129]
	v_mfma_f32_16x16x32_bf16 v[122:125], v[158:161], v[190:193], v[122:125]
	v_mfma_f32_16x16x32_bf16 v[118:121], v[150:153], v[198:201], v[118:121]
	v_mfma_f32_16x16x32_bf16 v[114:117], v[158:161], v[198:201], v[114:117]
	v_mfma_f32_16x16x32_bf16 v[102:105], v[150:153], v[206:209], v[102:105]
	v_mfma_f32_16x16x32_bf16 v[94:97], v[158:161], v[206:209], v[94:97]
	v_mfma_f32_16x16x32_bf16 v[86:89], v[150:153], v[214:217], v[86:89]
	v_mfma_f32_16x16x32_bf16 v[78:81], v[158:161], v[214:217], v[78:81]
	s_setprio 0
	s_setprio 1
	v_mfma_f32_16x16x32_bf16 v[110:113], v[162:165], v[186:189], v[110:113]
	v_mfma_f32_16x16x32_bf16 v[106:109], v[178:181], v[186:189], v[106:109]
	v_mfma_f32_16x16x32_bf16 v[98:101], v[162:165], v[194:197], v[98:101]
	v_mfma_f32_16x16x32_bf16 v[90:93], v[178:181], v[194:197], v[90:93]
	v_mfma_f32_16x16x32_bf16 v[82:85], v[162:165], v[202:205], v[82:85]
	v_mfma_f32_16x16x32_bf16 v[74:77], v[178:181], v[202:205], v[74:77]
	v_mfma_f32_16x16x32_bf16 v[70:73], v[162:165], v[210:213], v[70:73]
	v_mfma_f32_16x16x32_bf16 v[66:69], v[178:181], v[210:213], v[66:69]
	v_mfma_f32_16x16x32_bf16 v[110:113], v[174:177], v[190:193], v[110:113]
	v_mfma_f32_16x16x32_bf16 v[106:109], v[182:185], v[190:193], v[106:109]
	v_mfma_f32_16x16x32_bf16 v[98:101], v[174:177], v[198:201], v[98:101]
	v_mfma_f32_16x16x32_bf16 v[90:93], v[182:185], v[198:201], v[90:93]
	v_mfma_f32_16x16x32_bf16 v[82:85], v[174:177], v[206:209], v[82:85]
	v_mfma_f32_16x16x32_bf16 v[74:77], v[182:185], v[206:209], v[74:77]
	v_mfma_f32_16x16x32_bf16 v[70:73], v[174:177], v[214:217], v[70:73]
	v_mfma_f32_16x16x32_bf16 v[66:69], v[182:185], v[214:217], v[66:69]
	s_setprio 0
	s_barrier
	s_add_u32 s24, s22, 0x8000
	s_addc_u32 s25, s23, 0
	s_add_i32 s68, s68, s28
	v_lshl_add_u64 v[166:167], s[24:25], 0, v[132:133]
	s_mov_b32 m0, s68
	ds_read_b128 v[186:189], v173 offset:49152
	ds_read_b128 v[190:193], v173 offset:50176
	ds_read_b128 v[194:197], v173 offset:51200
	ds_read_b128 v[198:201], v173 offset:52224
	ds_read_b128 v[202:205], v173 offset:53248
	ds_read_b128 v[206:209], v173 offset:54272
	ds_read_b128 v[210:213], v173 offset:55296
	ds_read_b128 v[214:217], v173 offset:56320
	global_load_lds_dwordx4 v[166:167], off
	s_add_i32 m0, s68, 0x2000
	s_add_u32 s22, s22, 0xc000
	v_lshl_add_u64 v[166:167], s[24:25], 0, v[136:137]
	s_addc_u32 s23, s23, 0
	s_add_i32 s24, s69, s28
	global_load_lds_dwordx4 v[166:167], off
	v_lshl_add_u64 v[166:167], s[22:23], 0, v[132:133]
	s_mov_b32 m0, s24
	s_nop 0
	global_load_lds_dwordx4 v[166:167], off
	v_lshl_add_u64 v[166:167], s[22:23], 0, v[136:137]
	s_add_i32 m0, s24, 0x2000
	s_nop 0
	global_load_lds_dwordx4 v[166:167], off
	v_lshl_add_u64 v[166:167], s[20:21], 0, v[130:131]
	s_mov_b32 m0, s56
	s_nop 0
	global_load_lds_dwordx4 v[166:167], off
	v_lshl_add_u64 v[166:167], s[20:21], 0, v[134:135]
	s_mov_b32 m0, s57
	s_nop 0
	global_load_lds_dwordx4 v[166:167], off
	s_add_i32 s33, s33, 2
	s_add_u32 s18, s18, 0x10000
	s_addc_u32 s19, s19, 0
	s_add_u32 s30, s30, 0x10000
	s_addc_u32 s31, s31, 0
	s_cmpk_gt_u32 s33, 0x55
	s_waitcnt vmcnt(8)
	s_waitcnt lgkmcnt(0)
	s_barrier
	s_setprio 1
	s_waitcnt lgkmcnt(0)
	v_mfma_f32_16x16x32_bf16 v[62:65], v[146:149], v[186:189], v[62:65]
	v_mfma_f32_16x16x32_bf16 v[58:61], v[154:157], v[186:189], v[58:61]
	v_mfma_f32_16x16x32_bf16 v[54:57], v[146:149], v[194:197], v[54:57]
	v_mfma_f32_16x16x32_bf16 v[46:49], v[154:157], v[194:197], v[46:49]
	v_mfma_f32_16x16x32_bf16 v[38:41], v[146:149], v[202:205], v[38:41]
	v_mfma_f32_16x16x32_bf16 v[30:33], v[154:157], v[202:205], v[30:33]
	v_mfma_f32_16x16x32_bf16 v[22:25], v[146:149], v[210:213], v[22:25]
	v_mfma_f32_16x16x32_bf16 v[14:17], v[154:157], v[210:213], v[14:17]
	v_mfma_f32_16x16x32_bf16 v[62:65], v[150:153], v[190:193], v[62:65]
	v_mfma_f32_16x16x32_bf16 v[58:61], v[158:161], v[190:193], v[58:61]
	v_mfma_f32_16x16x32_bf16 v[54:57], v[150:153], v[198:201], v[54:57]
	v_mfma_f32_16x16x32_bf16 v[46:49], v[158:161], v[198:201], v[46:49]
	v_mfma_f32_16x16x32_bf16 v[38:41], v[150:153], v[206:209], v[38:41]
	v_mfma_f32_16x16x32_bf16 v[30:33], v[158:161], v[206:209], v[30:33]
	v_mfma_f32_16x16x32_bf16 v[22:25], v[150:153], v[214:217], v[22:25]
	v_mfma_f32_16x16x32_bf16 v[14:17], v[158:161], v[214:217], v[14:17]
	s_setprio 0
	s_setprio 1
	v_mfma_f32_16x16x32_bf16 v[50:53], v[162:165], v[186:189], v[50:53]
	v_mfma_f32_16x16x32_bf16 v[42:45], v[178:181], v[186:189], v[42:45]
	v_mfma_f32_16x16x32_bf16 v[34:37], v[162:165], v[194:197], v[34:37]
	v_mfma_f32_16x16x32_bf16 v[26:29], v[178:181], v[194:197], v[26:29]
	v_mfma_f32_16x16x32_bf16 v[18:21], v[162:165], v[202:205], v[18:21]
	v_mfma_f32_16x16x32_bf16 v[10:13], v[178:181], v[202:205], v[10:13]
	v_mfma_f32_16x16x32_bf16 v[6:9], v[162:165], v[210:213], v[6:9]
	v_mfma_f32_16x16x32_bf16 v[2:5], v[178:181], v[210:213], v[2:5]
	v_mfma_f32_16x16x32_bf16 v[50:53], v[174:177], v[190:193], v[50:53]
	v_mfma_f32_16x16x32_bf16 v[42:45], v[182:185], v[190:193], v[42:45]
	v_mfma_f32_16x16x32_bf16 v[34:37], v[174:177], v[198:201], v[34:37]
	v_mfma_f32_16x16x32_bf16 v[26:29], v[182:185], v[198:201], v[26:29]
	v_mfma_f32_16x16x32_bf16 v[18:21], v[174:177], v[206:209], v[18:21]
	v_mfma_f32_16x16x32_bf16 v[10:13], v[182:185], v[206:209], v[10:13]
	v_mfma_f32_16x16x32_bf16 v[6:9], v[174:177], v[214:217], v[6:9]
	v_mfma_f32_16x16x32_bf16 v[2:5], v[182:185], v[214:217], v[2:5]
	s_setprio 0
	s_barrier
	s_cbranch_scc1 .Lmy_rot3_exit
	ds_read_b128 v[146:149], v171
	ds_read_b128 v[150:153], v171 offset:1024
	ds_read_b128 v[154:157], v171 offset:2048
	ds_read_b128 v[158:161], v171 offset:3072
	ds_read_b128 v[162:165], v172
	ds_read_b128 v[174:177], v172 offset:1024
	ds_read_b128 v[178:181], v172 offset:2048
	ds_read_b128 v[182:185], v172 offset:3072
	s_branch .Lmy_rot3_head
.Lmy_rot3_exit:
	s_and_b64 vcc, exec, s[14:15]
	s_cbranch_vccz .LBB0_378
	s_barrier

.Lmy_rot5_head:
	s_add_u32 s31, s52, 0xfff80080
	s_addc_u32 s33, s53, -1
	s_cmp_eq_u32 s30, 28
	s_cselect_b32 s57, s9, s33
	s_cselect_b32 s56, s11, s31
	s_cselect_b32 s55, s25, s29
	s_cselect_b32 s54, s27, s28
	v_lshl_add_u64 v[176:177], s[52:53], 0, v[158:159]
	s_add_i32 m0, s61, 0xc000
	ds_read_b128 v[192:195], v182
	ds_read_b128 v[196:199], v182 offset:1024
	ds_read_b128 v[200:203], v182 offset:2048
	ds_read_b128 v[204:207], v182 offset:3072
	ds_read_b128 v[208:211], v182 offset:4096
	ds_read_b128 v[212:215], v182 offset:5120
	ds_read_b128 v[216:219], v182 offset:6144
	ds_read_b128 v[220:223], v182 offset:7168
	global_load_lds_dwordx4 v[176:177], off
	v_lshl_add_u64 v[176:177], s[52:53], 0, v[160:161]
	s_add_i32 m0, s61, 0xe000
	s_nop 0
	global_load_lds_dwordx4 v[176:177], off
	s_waitcnt vmcnt(8)
	s_waitcnt lgkmcnt(0)
	s_barrier
	s_setprio 1
	s_waitcnt lgkmcnt(0)
	v_mfma_f32_16x16x32_bf16 v[126:129], v[130:133], v[192:195], v[126:129]
	v_mfma_f32_16x16x32_bf16 v[122:125], v[138:141], v[192:195], v[122:125]
	v_mfma_f32_16x16x32_bf16 v[118:121], v[130:133], v[200:203], v[118:121]
	v_mfma_f32_16x16x32_bf16 v[110:113], v[138:141], v[200:203], v[110:113]
	v_mfma_f32_16x16x32_bf16 v[102:105], v[130:133], v[208:211], v[102:105]
	v_mfma_f32_16x16x32_bf16 v[94:97], v[138:141], v[208:211], v[94:97]
	v_mfma_f32_16x16x32_bf16 v[86:89], v[130:133], v[216:219], v[86:89]
	v_mfma_f32_16x16x32_bf16 v[78:81], v[138:141], v[216:219], v[78:81]
	v_mfma_f32_16x16x32_bf16 v[126:129], v[134:137], v[196:199], v[126:129]
	v_mfma_f32_16x16x32_bf16 v[122:125], v[142:145], v[196:199], v[122:125]
	v_mfma_f32_16x16x32_bf16 v[118:121], v[134:137], v[204:207], v[118:121]
	v_mfma_f32_16x16x32_bf16 v[110:113], v[142:145], v[204:207], v[110:113]
	v_mfma_f32_16x16x32_bf16 v[102:105], v[134:137], v[212:215], v[102:105]
	v_mfma_f32_16x16x32_bf16 v[94:97], v[142:145], v[212:215], v[94:97]
	v_mfma_f32_16x16x32_bf16 v[86:89], v[134:137], v[220:223], v[86:89]
	v_mfma_f32_16x16x32_bf16 v[78:81], v[142:145], v[220:223], v[78:81]
	s_setprio 0
	s_setprio 1
	v_mfma_f32_16x16x32_bf16 v[114:117], v[168:171], v[192:195], v[114:117]
	v_mfma_f32_16x16x32_bf16 v[106:109], v[184:187], v[192:195], v[106:109]
	v_mfma_f32_16x16x32_bf16 v[98:101], v[168:171], v[200:203], v[98:101]
	v_mfma_f32_16x16x32_bf16 v[90:93], v[184:187], v[200:203], v[90:93]
	v_mfma_f32_16x16x32_bf16 v[82:85], v[168:171], v[208:211], v[82:85]
	v_mfma_f32_16x16x32_bf16 v[74:77], v[184:187], v[208:211], v[74:77]
	v_mfma_f32_16x16x32_bf16 v[70:73], v[168:171], v[216:219], v[70:73]
	v_mfma_f32_16x16x32_bf16 v[66:69], v[184:187], v[216:219], v[66:69]
	v_mfma_f32_16x16x32_bf16 v[114:117], v[172:175], v[196:199], v[114:117]
	v_mfma_f32_16x16x32_bf16 v[106:109], v[188:191], v[196:199], v[106:109]
	v_mfma_f32_16x16x32_bf16 v[98:101], v[172:175], v[204:207], v[98:101]
	v_mfma_f32_16x16x32_bf16 v[90:93], v[188:191], v[204:207], v[90:93]
	v_mfma_f32_16x16x32_bf16 v[82:85], v[172:175], v[212:215], v[82:85]
	v_mfma_f32_16x16x32_bf16 v[74:77], v[188:191], v[212:215], v[74:77]
	v_mfma_f32_16x16x32_bf16 v[70:73], v[172:175], v[220:223], v[70:73]
	v_mfma_f32_16x16x32_bf16 v[66:69], v[188:191], v[220:223], v[66:69]
	s_setprio 0
	s_barrier
	s_add_i32 s31, s89, s60
	v_lshl_add_u64 v[176:177], s[54:55], 0, v[148:149]
	s_mov_b32 m0, s31
	ds_read_b128 v[192:195], v182 offset:16384
	ds_read_b128 v[196:199], v182 offset:17408
	ds_read_b128 v[200:203], v182 offset:18432
	ds_read_b128 v[204:207], v182 offset:19456
	ds_read_b128 v[208:211], v182 offset:20480
	ds_read_b128 v[212:215], v182 offset:21504
	ds_read_b128 v[216:219], v182 offset:22528
	ds_read_b128 v[220:223], v182 offset:23552
	global_load_lds_dwordx4 v[176:177], off
	s_add_i32 m0, s31, 0x2000
	s_add_u32 s34, s54, 0x4000
	v_lshl_add_u64 v[176:177], s[54:55], 0, v[152:153]
	s_addc_u32 s35, s55, 0
	s_add_i32 s31, s90, s60
	global_load_lds_dwordx4 v[176:177], off
	v_lshl_add_u64 v[176:177], s[34:35], 0, v[148:149]
	s_mov_b32 m0, s31
	v_lshl_add_u64 v[224:225], s[56:57], 0, v[150:151]
	global_load_lds_dwordx4 v[176:177], off
	v_lshl_add_u64 v[176:177], s[34:35], 0, v[152:153]
	s_add_i32 m0, s31, 0x2000
	s_nop 0
	global_load_lds_dwordx4 v[176:177], off
	v_lshl_add_u64 v[176:177], s[56:57], 0, v[146:147]
	s_mov_b32 m0, s61
	s_nop 0
	global_load_lds_dwordx4 v[176:177], off
	s_mov_b32 m0, s62
	s_nop 0
	global_load_lds_dwordx4 v[224:225], off
	s_waitcnt vmcnt(8)
	s_waitcnt lgkmcnt(0)
	s_barrier
	s_setprio 1
	s_waitcnt lgkmcnt(0)
	v_mfma_f32_16x16x32_bf16 v[62:65], v[130:133], v[192:195], v[62:65]
	v_mfma_f32_16x16x32_bf16 v[58:61], v[138:141], v[192:195], v[58:61]
	v_mfma_f32_16x16x32_bf16 v[54:57], v[130:133], v[200:203], v[54:57]
	v_mfma_f32_16x16x32_bf16 v[46:49], v[138:141], v[200:203], v[46:49]
	v_mfma_f32_16x16x32_bf16 v[38:41], v[130:133], v[208:211], v[38:41]
	v_mfma_f32_16x16x32_bf16 v[30:33], v[138:141], v[208:211], v[30:33]
	v_mfma_f32_16x16x32_bf16 v[22:25], v[130:133], v[216:219], v[22:25]
	v_mfma_f32_16x16x32_bf16 v[14:17], v[138:141], v[216:219], v[14:17]
	v_mfma_f32_16x16x32_bf16 v[62:65], v[134:137], v[196:199], v[62:65]
	v_mfma_f32_16x16x32_bf16 v[58:61], v[142:145], v[196:199], v[58:61]
	v_mfma_f32_16x16x32_bf16 v[54:57], v[134:137], v[204:207], v[54:57]
	v_mfma_f32_16x16x32_bf16 v[46:49], v[142:145], v[204:207], v[46:49]
	v_mfma_f32_16x16x32_bf16 v[38:41], v[134:137], v[212:215], v[38:41]
	v_mfma_f32_16x16x32_bf16 v[30:33], v[142:145], v[212:215], v[30:33]
	v_mfma_f32_16x16x32_bf16 v[22:25], v[134:137], v[220:223], v[22:25]
	v_mfma_f32_16x16x32_bf16 v[14:17], v[142:145], v[220:223], v[14:17]
	s_setprio 0
	s_setprio 1
	v_mfma_f32_16x16x32_bf16 v[50:53], v[168:171], v[192:195], v[50:53]
	v_mfma_f32_16x16x32_bf16 v[42:45], v[184:187], v[192:195], v[42:45]
	v_mfma_f32_16x16x32_bf16 v[34:37], v[168:171], v[200:203], v[34:37]
	v_mfma_f32_16x16x32_bf16 v[26:29], v[184:187], v[200:203], v[26:29]
	v_mfma_f32_16x16x32_bf16 v[18:21], v[168:171], v[208:211], v[18:21]
	v_mfma_f32_16x16x32_bf16 v[10:13], v[184:187], v[208:211], v[10:13]
	v_mfma_f32_16x16x32_bf16 v[6:9], v[168:171], v[216:219], v[6:9]
	v_mfma_f32_16x16x32_bf16 v[2:5], v[184:187], v[216:219], v[2:5]
	v_mfma_f32_16x16x32_bf16 v[50:53], v[172:175], v[196:199], v[50:53]
	v_mfma_f32_16x16x32_bf16 v[42:45], v[188:191], v[196:199], v[42:45]
	v_mfma_f32_16x16x32_bf16 v[34:37], v[172:175], v[204:207], v[34:37]
	v_mfma_f32_16x16x32_bf16 v[26:29], v[188:191], v[204:207], v[26:29]
	v_mfma_f32_16x16x32_bf16 v[18:21], v[172:175], v[212:215], v[18:21]
	v_mfma_f32_16x16x32_bf16 v[10:13], v[188:191], v[212:215], v[10:13]
	v_mfma_f32_16x16x32_bf16 v[6:9], v[172:175], v[220:223], v[6:9]
	v_mfma_f32_16x16x32_bf16 v[2:5], v[188:191], v[220:223], v[2:5]
	s_setprio 0
	s_barrier
	s_add_i32 s31, 0, 0x18000
	s_add_i32 s33, 0, 0x1c000
	v_add_u32_e32 v142, s31, v178
	v_add_u32_e32 v154, s33, v178
	ds_read_b128 v[130:133], v142
	ds_read_b128 v[134:137], v142 offset:1024
	ds_read_b128 v[138:141], v142 offset:2048
	ds_read_b128 v[142:145], v142 offset:3072
	ds_read_b128 v[168:171], v154
	ds_read_b128 v[172:175], v154 offset:1024
	ds_read_b128 v[184:187], v154 offset:2048
	ds_read_b128 v[188:191], v154 offset:3072
	s_add_u32 s34, s56, 0x80000
	s_addc_u32 s35, s57, 0
	s_mov_b32 m0, s63
	v_lshl_add_u64 v[226:227], s[34:35], 0, v[146:147]
	ds_read_b128 v[192:195], v182 offset:32768
	ds_read_b128 v[196:199], v182 offset:33792
	ds_read_b128 v[200:203], v182 offset:34816
	ds_read_b128 v[204:207], v182 offset:35840
	ds_read_b128 v[208:211], v182 offset:36864
	ds_read_b128 v[212:215], v182 offset:37888
	ds_read_b128 v[216:219], v182 offset:38912
	ds_read_b128 v[220:223], v182 offset:39936
	global_load_lds_dwordx4 v[226:227], off
	v_lshl_add_u64 v[226:227], s[34:35], 0, v[150:151]
	s_mov_b32 m0, s71
	s_nop 0
	global_load_lds_dwordx4 v[226:227], off
	s_waitcnt vmcnt(8)
	s_waitcnt lgkmcnt(0)
	s_barrier
	s_setprio 1
	s_waitcnt lgkmcnt(0)
	v_mfma_f32_16x16x32_bf16 v[126:129], v[130:133], v[192:195], v[126:129]
	v_mfma_f32_16x16x32_bf16 v[122:125], v[138:141], v[192:195], v[122:125]
	v_mfma_f32_16x16x32_bf16 v[118:121], v[130:133], v[200:203], v[118:121]
	v_mfma_f32_16x16x32_bf16 v[110:113], v[138:141], v[200:203], v[110:113]
	v_mfma_f32_16x16x32_bf16 v[102:105], v[130:133], v[208:211], v[102:105]
	v_mfma_f32_16x16x32_bf16 v[94:97], v[138:141], v[208:211], v[94:97]
	v_mfma_f32_16x16x32_bf16 v[86:89], v[130:133], v[216:219], v[86:89]
	v_mfma_f32_16x16x32_bf16 v[78:81], v[138:141], v[216:219], v[78:81]
	v_mfma_f32_16x16x32_bf16 v[126:129], v[134:137], v[196:199], v[126:129]
	v_mfma_f32_16x16x32_bf16 v[122:125], v[142:145], v[196:199], v[122:125]
	v_mfma_f32_16x16x32_bf16 v[118:121], v[134:137], v[204:207], v[118:121]
	v_mfma_f32_16x16x32_bf16 v[110:113], v[142:145], v[204:207], v[110:113]
	v_mfma_f32_16x16x32_bf16 v[102:105], v[134:137], v[212:215], v[102:105]
	v_mfma_f32_16x16x32_bf16 v[94:97], v[142:145], v[212:215], v[94:97]
	v_mfma_f32_16x16x32_bf16 v[86:89], v[134:137], v[220:223], v[86:89]
	v_mfma_f32_16x16x32_bf16 v[78:81], v[142:145], v[220:223], v[78:81]
	s_setprio 0
	s_setprio 1
	v_mfma_f32_16x16x32_bf16 v[114:117], v[168:171], v[192:195], v[114:117]
	v_mfma_f32_16x16x32_bf16 v[106:109], v[184:187], v[192:195], v[106:109]
	v_mfma_f32_16x16x32_bf16 v[98:101], v[168:171], v[200:203], v[98:101]
	v_mfma_f32_16x16x32_bf16 v[90:93], v[184:187], v[200:203], v[90:93]
	v_mfma_f32_16x16x32_bf16 v[82:85], v[168:171], v[208:211], v[82:85]
	v_mfma_f32_16x16x32_bf16 v[74:77], v[184:187], v[208:211], v[74:77]
	v_mfma_f32_16x16x32_bf16 v[70:73], v[168:171], v[216:219], v[70:73]
	v_mfma_f32_16x16x32_bf16 v[66:69], v[184:187], v[216:219], v[66:69]
	v_mfma_f32_16x16x32_bf16 v[114:117], v[172:175], v[196:199], v[114:117]
	v_mfma_f32_16x16x32_bf16 v[106:109], v[188:191], v[196:199], v[106:109]
	v_mfma_f32_16x16x32_bf16 v[98:101], v[172:175], v[204:207], v[98:101]
	v_mfma_f32_16x16x32_bf16 v[90:93], v[188:191], v[204:207], v[90:93]
	v_mfma_f32_16x16x32_bf16 v[82:85], v[172:175], v[212:215], v[82:85]
	v_mfma_f32_16x16x32_bf16 v[74:77], v[188:191], v[212:215], v[74:77]
	v_mfma_f32_16x16x32_bf16 v[70:73], v[172:175], v[220:223], v[70:73]
	v_mfma_f32_16x16x32_bf16 v[66:69], v[188:191], v[220:223], v[66:69]
	s_setprio 0
	s_barrier
	s_add_u32 s34, s54, 0x8000
	s_addc_u32 s35, s55, 0
	s_add_i32 s31, s31, s60
	v_lshl_add_u64 v[226:227], s[34:35], 0, v[148:149]
	s_mov_b32 m0, s31
	ds_read_b128 v[192:195], v182 offset:49152
	ds_read_b128 v[196:199], v182 offset:50176
	ds_read_b128 v[200:203], v182 offset:51200
	ds_read_b128 v[204:207], v182 offset:52224
	ds_read_b128 v[208:211], v182 offset:53248
	ds_read_b128 v[212:215], v182 offset:54272
	ds_read_b128 v[216:219], v182 offset:55296
	ds_read_b128 v[220:223], v182 offset:56320
	global_load_lds_dwordx4 v[226:227], off
	s_add_i32 m0, s31, 0x2000
	v_lshl_add_u64 v[226:227], s[34:35], 0, v[152:153]
	s_add_u32 s34, s54, 0xc000
	s_addc_u32 s35, s55, 0
	s_add_i32 s31, s33, s60
	global_load_lds_dwordx4 v[226:227], off
	v_lshl_add_u64 v[226:227], s[34:35], 0, v[148:149]
	s_mov_b32 m0, s31
	v_lshl_add_u64 v[176:177], v[176:177], 0, s[18:19]
	global_load_lds_dwordx4 v[226:227], off
	v_lshl_add_u64 v[226:227], s[34:35], 0, v[152:153]
	s_add_i32 m0, s31, 0x2000
	s_nop 0
	global_load_lds_dwordx4 v[226:227], off
	s_mov_b32 m0, s87
	s_nop 0
	global_load_lds_dwordx4 v[176:177], off
	v_lshl_add_u64 v[176:177], v[224:225], 0, s[18:19]
	s_mov_b32 m0, s88
	s_nop 0
	global_load_lds_dwordx4 v[176:177], off
	s_add_i32 s30, s30, 2
	s_add_u32 s28, s28, 0x10000
	s_addc_u32 s29, s29, 0
	s_add_u32 s52, s52, 0x100
	s_addc_u32 s53, s53, 0
	s_cmp_gt_u32 s30, 29
	s_waitcnt vmcnt(8)
	s_waitcnt lgkmcnt(0)
	s_barrier
	s_setprio 1
	s_waitcnt lgkmcnt(0)
	v_mfma_f32_16x16x32_bf16 v[62:65], v[130:133], v[192:195], v[62:65]
	v_mfma_f32_16x16x32_bf16 v[58:61], v[138:141], v[192:195], v[58:61]
	v_mfma_f32_16x16x32_bf16 v[54:57], v[130:133], v[200:203], v[54:57]
	v_mfma_f32_16x16x32_bf16 v[46:49], v[138:141], v[200:203], v[46:49]
	v_mfma_f32_16x16x32_bf16 v[38:41], v[130:133], v[208:211], v[38:41]
	v_mfma_f32_16x16x32_bf16 v[30:33], v[138:141], v[208:211], v[30:33]
	v_mfma_f32_16x16x32_bf16 v[22:25], v[130:133], v[216:219], v[22:25]
	v_mfma_f32_16x16x32_bf16 v[14:17], v[138:141], v[216:219], v[14:17]
	v_mfma_f32_16x16x32_bf16 v[62:65], v[134:137], v[196:199], v[62:65]
	v_mfma_f32_16x16x32_bf16 v[58:61], v[142:145], v[196:199], v[58:61]
	v_mfma_f32_16x16x32_bf16 v[54:57], v[134:137], v[204:207], v[54:57]
	v_mfma_f32_16x16x32_bf16 v[46:49], v[142:145], v[204:207], v[46:49]
	v_mfma_f32_16x16x32_bf16 v[38:41], v[134:137], v[212:215], v[38:41]
	v_mfma_f32_16x16x32_bf16 v[30:33], v[142:145], v[212:215], v[30:33]
	v_mfma_f32_16x16x32_bf16 v[22:25], v[134:137], v[220:223], v[22:25]
	v_mfma_f32_16x16x32_bf16 v[14:17], v[142:145], v[220:223], v[14:17]
	s_setprio 0
	s_setprio 1
	v_mfma_f32_16x16x32_bf16 v[50:53], v[168:171], v[192:195], v[50:53]
	v_mfma_f32_16x16x32_bf16 v[42:45], v[184:187], v[192:195], v[42:45]
	v_mfma_f32_16x16x32_bf16 v[34:37], v[168:171], v[200:203], v[34:37]
	v_mfma_f32_16x16x32_bf16 v[26:29], v[184:187], v[200:203], v[26:29]
	v_mfma_f32_16x16x32_bf16 v[18:21], v[168:171], v[208:211], v[18:21]
	v_mfma_f32_16x16x32_bf16 v[10:13], v[184:187], v[208:211], v[10:13]
	v_mfma_f32_16x16x32_bf16 v[6:9], v[168:171], v[216:219], v[6:9]
	v_mfma_f32_16x16x32_bf16 v[2:5], v[184:187], v[216:219], v[2:5]
	v_mfma_f32_16x16x32_bf16 v[50:53], v[172:175], v[196:199], v[50:53]
	v_mfma_f32_16x16x32_bf16 v[42:45], v[188:191], v[196:199], v[42:45]
	v_mfma_f32_16x16x32_bf16 v[34:37], v[172:175], v[204:207], v[34:37]
	v_mfma_f32_16x16x32_bf16 v[26:29], v[188:191], v[204:207], v[26:29]
	v_mfma_f32_16x16x32_bf16 v[18:21], v[172:175], v[212:215], v[18:21]
	v_mfma_f32_16x16x32_bf16 v[10:13], v[188:191], v[212:215], v[10:13]
	v_mfma_f32_16x16x32_bf16 v[6:9], v[172:175], v[220:223], v[6:9]
	v_mfma_f32_16x16x32_bf16 v[2:5], v[188:191], v[220:223], v[2:5]
	s_setprio 0
	s_barrier
	s_cbranch_scc1 .Lmy_rot5_exit
	ds_read_b128 v[130:133], v180
	ds_read_b128 v[134:137], v180 offset:1024
	ds_read_b128 v[138:141], v180 offset:2048
	ds_read_b128 v[142:145], v180 offset:3072
	ds_read_b128 v[168:171], v181
	ds_read_b128 v[172:175], v181 offset:1024
	ds_read_b128 v[184:187], v181 offset:2048
	ds_read_b128 v[188:191], v181 offset:3072
	s_branch .Lmy_rot5_head
.Lmy_rot5_exit:
	s_and_b64 vcc, exec, s[20:21]
	s_cbranch_vccz .LBB0_509
	s_barrier

.Lmy_rot8_head:
	s_add_u32 s52, s44, 0xfff80080
	s_addc_u32 s53, s45, -1
	s_cmp_eq_u32 s69, 28
	s_cselect_b32 s55, s25, s53
	s_cselect_b32 s54, s68, s52
	s_cselect_b32 s53, s23, s31
	s_cselect_b32 s52, s33, s30
	v_lshl_add_u64 v[216:217], s[44:45], 0, v[154:155]
	s_add_i32 m0, s43, 0xc000
	ds_read_b128 v[184:187], v175
	ds_read_b128 v[188:191], v175 offset:1024
	ds_read_b128 v[192:195], v175 offset:2048
	ds_read_b128 v[196:199], v175 offset:3072
	ds_read_b128 v[200:203], v175 offset:4096
	ds_read_b128 v[204:207], v175 offset:5120
	ds_read_b128 v[208:211], v175 offset:6144
	ds_read_b128 v[212:215], v175 offset:7168
	global_load_lds_dwordx4 v[216:217], off
	v_lshl_add_u64 v[216:217], s[44:45], 0, v[156:157]
	s_add_i32 m0, s43, 0xe000
	s_nop 0
	global_load_lds_dwordx4 v[216:217], off
	s_waitcnt vmcnt(8)
	s_waitcnt lgkmcnt(0)
	s_barrier
	s_setprio 1
	s_waitcnt lgkmcnt(0)
	v_mfma_f32_16x16x32_bf16 v[126:129], v[130:133], v[184:187], v[126:129]
	v_mfma_f32_16x16x32_bf16 v[122:125], v[138:141], v[184:187], v[122:125]
	v_mfma_f32_16x16x32_bf16 v[118:121], v[130:133], v[192:195], v[118:121]
	v_mfma_f32_16x16x32_bf16 v[114:117], v[138:141], v[192:195], v[114:117]
	v_mfma_f32_16x16x32_bf16 v[94:97], v[130:133], v[200:203], v[94:97]
	v_mfma_f32_16x16x32_bf16 v[90:93], v[138:141], v[200:203], v[90:93]
	v_mfma_f32_16x16x32_bf16 v[78:81], v[130:133], v[208:211], v[78:81]
	v_mfma_f32_16x16x32_bf16 v[74:77], v[138:141], v[208:211], v[74:77]
	v_mfma_f32_16x16x32_bf16 v[126:129], v[134:137], v[188:191], v[126:129]
	v_mfma_f32_16x16x32_bf16 v[122:125], v[142:145], v[188:191], v[122:125]
	v_mfma_f32_16x16x32_bf16 v[118:121], v[134:137], v[196:199], v[118:121]
	v_mfma_f32_16x16x32_bf16 v[114:117], v[142:145], v[196:199], v[114:117]
	v_mfma_f32_16x16x32_bf16 v[94:97], v[134:137], v[204:207], v[94:97]
	v_mfma_f32_16x16x32_bf16 v[90:93], v[142:145], v[204:207], v[90:93]
	v_mfma_f32_16x16x32_bf16 v[78:81], v[134:137], v[212:215], v[78:81]
	v_mfma_f32_16x16x32_bf16 v[74:77], v[142:145], v[212:215], v[74:77]
	s_setprio 0
	s_setprio 1
	v_mfma_f32_16x16x32_bf16 v[110:113], v[162:165], v[184:187], v[110:113]
	v_mfma_f32_16x16x32_bf16 v[106:109], v[176:179], v[184:187], v[106:109]
	v_mfma_f32_16x16x32_bf16 v[102:105], v[162:165], v[192:195], v[102:105]
	v_mfma_f32_16x16x32_bf16 v[98:101], v[176:179], v[192:195], v[98:101]
	v_mfma_f32_16x16x32_bf16 v[86:89], v[162:165], v[200:203], v[86:89]
	v_mfma_f32_16x16x32_bf16 v[82:85], v[176:179], v[200:203], v[82:85]
	v_mfma_f32_16x16x32_bf16 v[70:73], v[162:165], v[208:211], v[70:73]
	v_mfma_f32_16x16x32_bf16 v[66:69], v[176:179], v[208:211], v[66:69]
	v_mfma_f32_16x16x32_bf16 v[110:113], v[166:169], v[188:191], v[110:113]
	v_mfma_f32_16x16x32_bf16 v[106:109], v[180:183], v[188:191], v[106:109]
	v_mfma_f32_16x16x32_bf16 v[102:105], v[166:169], v[196:199], v[102:105]
	v_mfma_f32_16x16x32_bf16 v[98:101], v[180:183], v[196:199], v[98:101]
	v_mfma_f32_16x16x32_bf16 v[86:89], v[166:169], v[204:207], v[86:89]
	v_mfma_f32_16x16x32_bf16 v[82:85], v[180:183], v[204:207], v[82:85]
	v_mfma_f32_16x16x32_bf16 v[70:73], v[166:169], v[212:215], v[70:73]
	v_mfma_f32_16x16x32_bf16 v[66:69], v[180:183], v[212:215], v[66:69]
	s_setprio 0
	s_barrier
	s_add_i32 s71, s65, s35
	v_lshl_add_u64 v[216:217], s[52:53], 0, v[148:149]
	s_mov_b32 m0, s71
	ds_read_b128 v[184:187], v175 offset:16384
	ds_read_b128 v[188:191], v175 offset:17408
	ds_read_b128 v[192:195], v175 offset:18432
	ds_read_b128 v[196:199], v175 offset:19456
	ds_read_b128 v[200:203], v175 offset:20480
	ds_read_b128 v[204:207], v175 offset:21504
	ds_read_b128 v[208:211], v175 offset:22528
	ds_read_b128 v[212:215], v175 offset:23552
	global_load_lds_dwordx4 v[216:217], off
	s_add_i32 m0, s71, 0x2000
	s_add_u32 s74, s52, 0x4000
	v_lshl_add_u64 v[216:217], s[52:53], 0, v[152:153]
	s_addc_u32 s75, s53, 0
	s_add_i32 s71, s66, s35
	global_load_lds_dwordx4 v[216:217], off
	v_lshl_add_u64 v[216:217], s[74:75], 0, v[148:149]
	s_mov_b32 m0, s71
	v_lshl_add_u64 v[218:219], s[54:55], 0, v[150:151]
	global_load_lds_dwordx4 v[216:217], off
	v_lshl_add_u64 v[216:217], s[74:75], 0, v[152:153]
	s_add_i32 m0, s71, 0x2000
	s_nop 0
	global_load_lds_dwordx4 v[216:217], off
	v_lshl_add_u64 v[216:217], s[54:55], 0, v[146:147]
	s_mov_b32 m0, s43
	s_nop 0
	global_load_lds_dwordx4 v[216:217], off
	s_mov_b32 m0, s56
	s_nop 0
	global_load_lds_dwordx4 v[218:219], off
	s_waitcnt vmcnt(8)
	s_waitcnt lgkmcnt(0)
	s_barrier
	s_setprio 1
	s_waitcnt lgkmcnt(0)
	v_mfma_f32_16x16x32_bf16 v[62:65], v[130:133], v[184:187], v[62:65]
	v_mfma_f32_16x16x32_bf16 v[58:61], v[138:141], v[184:187], v[58:61]
	v_mfma_f32_16x16x32_bf16 v[46:49], v[130:133], v[192:195], v[46:49]
	v_mfma_f32_16x16x32_bf16 v[42:45], v[138:141], v[192:195], v[42:45]
	v_mfma_f32_16x16x32_bf16 v[30:33], v[130:133], v[200:203], v[30:33]
	v_mfma_f32_16x16x32_bf16 v[26:29], v[138:141], v[200:203], v[26:29]
	v_mfma_f32_16x16x32_bf16 v[14:17], v[130:133], v[208:211], v[14:17]
	v_mfma_f32_16x16x32_bf16 v[10:13], v[138:141], v[208:211], v[10:13]
	v_mfma_f32_16x16x32_bf16 v[62:65], v[134:137], v[188:191], v[62:65]
	v_mfma_f32_16x16x32_bf16 v[58:61], v[142:145], v[188:191], v[58:61]
	v_mfma_f32_16x16x32_bf16 v[46:49], v[134:137], v[196:199], v[46:49]
	v_mfma_f32_16x16x32_bf16 v[42:45], v[142:145], v[196:199], v[42:45]
	v_mfma_f32_16x16x32_bf16 v[30:33], v[134:137], v[204:207], v[30:33]
	v_mfma_f32_16x16x32_bf16 v[26:29], v[142:145], v[204:207], v[26:29]
	v_mfma_f32_16x16x32_bf16 v[14:17], v[134:137], v[212:215], v[14:17]
	v_mfma_f32_16x16x32_bf16 v[10:13], v[142:145], v[212:215], v[10:13]
	s_setprio 0
	s_setprio 1
	v_mfma_f32_16x16x32_bf16 v[54:57], v[162:165], v[184:187], v[54:57]
	v_mfma_f32_16x16x32_bf16 v[50:53], v[176:179], v[184:187], v[50:53]
	v_mfma_f32_16x16x32_bf16 v[38:41], v[162:165], v[192:195], v[38:41]
	v_mfma_f32_16x16x32_bf16 v[34:37], v[176:179], v[192:195], v[34:37]
	v_mfma_f32_16x16x32_bf16 v[22:25], v[162:165], v[200:203], v[22:25]
	v_mfma_f32_16x16x32_bf16 v[18:21], v[176:179], v[200:203], v[18:21]
	v_mfma_f32_16x16x32_bf16 v[6:9], v[162:165], v[208:211], v[6:9]
	v_mfma_f32_16x16x32_bf16 v[2:5], v[176:179], v[208:211], v[2:5]
	v_mfma_f32_16x16x32_bf16 v[54:57], v[166:169], v[188:191], v[54:57]
	v_mfma_f32_16x16x32_bf16 v[50:53], v[180:183], v[188:191], v[50:53]
	v_mfma_f32_16x16x32_bf16 v[38:41], v[166:169], v[196:199], v[38:41]
	v_mfma_f32_16x16x32_bf16 v[34:37], v[180:183], v[196:199], v[34:37]
	v_mfma_f32_16x16x32_bf16 v[22:25], v[166:169], v[204:207], v[22:25]
	v_mfma_f32_16x16x32_bf16 v[18:21], v[180:183], v[204:207], v[18:21]
	v_mfma_f32_16x16x32_bf16 v[6:9], v[166:169], v[212:215], v[6:9]
	v_mfma_f32_16x16x32_bf16 v[2:5], v[180:183], v[212:215], v[2:5]
	s_setprio 0
	s_barrier
	s_add_i32 s71, 0, 0x18000
	s_add_i32 s73, 0, 0x1c000
	v_add_u32_e32 v142, s71, v171
	v_add_u32_e32 v180, s73, v171
	ds_read_b128 v[130:133], v142
	ds_read_b128 v[134:137], v142 offset:1024
	ds_read_b128 v[138:141], v142 offset:2048
	ds_read_b128 v[142:145], v142 offset:3072
	ds_read_b128 v[162:165], v180
	ds_read_b128 v[166:169], v180 offset:1024
	ds_read_b128 v[176:179], v180 offset:2048
	ds_read_b128 v[180:183], v180 offset:3072
	s_add_u32 s54, s54, 0x80000
	s_addc_u32 s55, s55, 0
	s_mov_b32 m0, s57
	v_lshl_add_u64 v[220:221], s[54:55], 0, v[146:147]
	ds_read_b128 v[184:187], v175 offset:32768
	ds_read_b128 v[188:191], v175 offset:33792
	ds_read_b128 v[192:195], v175 offset:34816
	ds_read_b128 v[196:199], v175 offset:35840
	ds_read_b128 v[200:203], v175 offset:36864
	ds_read_b128 v[204:207], v175 offset:37888
	ds_read_b128 v[208:211], v175 offset:38912
	ds_read_b128 v[212:215], v175 offset:39936
	global_load_lds_dwordx4 v[220:221], off
	v_lshl_add_u64 v[220:221], s[54:55], 0, v[150:151]
	s_mov_b32 m0, s58
	s_nop 0
	global_load_lds_dwordx4 v[220:221], off
	s_waitcnt vmcnt(8)
	s_waitcnt lgkmcnt(0)
	s_barrier
	s_setprio 1
	s_waitcnt lgkmcnt(0)
	v_mfma_f32_16x16x32_bf16 v[126:129], v[130:133], v[184:187], v[126:129]
	v_mfma_f32_16x16x32_bf16 v[122:125], v[138:141], v[184:187], v[122:125]
	v_mfma_f32_16x16x32_bf16 v[118:121], v[130:133], v[192:195], v[118:121]
	v_mfma_f32_16x16x32_bf16 v[114:117], v[138:141], v[192:195], v[114:117]
	v_mfma_f32_16x16x32_bf16 v[94:97], v[130:133], v[200:203], v[94:97]
	v_mfma_f32_16x16x32_bf16 v[90:93], v[138:141], v[200:203], v[90:93]
	v_mfma_f32_16x16x32_bf16 v[78:81], v[130:133], v[208:211], v[78:81]
	v_mfma_f32_16x16x32_bf16 v[74:77], v[138:141], v[208:211], v[74:77]
	v_mfma_f32_16x16x32_bf16 v[126:129], v[134:137], v[188:191], v[126:129]
	v_mfma_f32_16x16x32_bf16 v[122:125], v[142:145], v[188:191], v[122:125]
	v_mfma_f32_16x16x32_bf16 v[118:121], v[134:137], v[196:199], v[118:121]
	v_mfma_f32_16x16x32_bf16 v[114:117], v[142:145], v[196:199], v[114:117]
	v_mfma_f32_16x16x32_bf16 v[94:97], v[134:137], v[204:207], v[94:97]
	v_mfma_f32_16x16x32_bf16 v[90:93], v[142:145], v[204:207], v[90:93]
	v_mfma_f32_16x16x32_bf16 v[78:81], v[134:137], v[212:215], v[78:81]
	v_mfma_f32_16x16x32_bf16 v[74:77], v[142:145], v[212:215], v[74:77]
	s_setprio 0
	s_setprio 1
	v_mfma_f32_16x16x32_bf16 v[110:113], v[162:165], v[184:187], v[110:113]
	v_mfma_f32_16x16x32_bf16 v[106:109], v[176:179], v[184:187], v[106:109]
	v_mfma_f32_16x16x32_bf16 v[102:105], v[162:165], v[192:195], v[102:105]
	v_mfma_f32_16x16x32_bf16 v[98:101], v[176:179], v[192:195], v[98:101]
	v_mfma_f32_16x16x32_bf16 v[86:89], v[162:165], v[200:203], v[86:89]
	v_mfma_f32_16x16x32_bf16 v[82:85], v[176:179], v[200:203], v[82:85]
	v_mfma_f32_16x16x32_bf16 v[70:73], v[162:165], v[208:211], v[70:73]
	v_mfma_f32_16x16x32_bf16 v[66:69], v[176:179], v[208:211], v[66:69]
	v_mfma_f32_16x16x32_bf16 v[110:113], v[166:169], v[188:191], v[110:113]
	v_mfma_f32_16x16x32_bf16 v[106:109], v[180:183], v[188:191], v[106:109]
	v_mfma_f32_16x16x32_bf16 v[102:105], v[166:169], v[196:199], v[102:105]
	v_mfma_f32_16x16x32_bf16 v[98:101], v[180:183], v[196:199], v[98:101]
	v_mfma_f32_16x16x32_bf16 v[86:89], v[166:169], v[204:207], v[86:89]
	v_mfma_f32_16x16x32_bf16 v[82:85], v[180:183], v[204:207], v[82:85]
	v_mfma_f32_16x16x32_bf16 v[70:73], v[166:169], v[212:215], v[70:73]
	v_mfma_f32_16x16x32_bf16 v[66:69], v[180:183], v[212:215], v[66:69]
	s_setprio 0
	s_barrier
	s_add_u32 s54, s52, 0x8000
	s_addc_u32 s55, s53, 0
	s_add_i32 s71, s71, s35
	v_lshl_add_u64 v[220:221], s[54:55], 0, v[148:149]
	s_mov_b32 m0, s71
	ds_read_b128 v[184:187], v175 offset:49152
	ds_read_b128 v[188:191], v175 offset:50176
	ds_read_b128 v[192:195], v175 offset:51200
	ds_read_b128 v[196:199], v175 offset:52224
	ds_read_b128 v[200:203], v175 offset:53248
	ds_read_b128 v[204:207], v175 offset:54272
	ds_read_b128 v[208:211], v175 offset:55296
	ds_read_b128 v[212:215], v175 offset:56320
	global_load_lds_dwordx4 v[220:221], off
	s_add_i32 m0, s71, 0x2000
	s_add_u32 s52, s52, 0xc000
	v_lshl_add_u64 v[220:221], s[54:55], 0, v[152:153]
	s_addc_u32 s53, s53, 0
	s_add_i32 s54, s73, s35
	global_load_lds_dwordx4 v[220:221], off
	v_lshl_add_u64 v[220:221], s[52:53], 0, v[148:149]
	s_mov_b32 m0, s54
	v_lshl_add_u64 v[216:217], v[216:217], 0, s[12:13]
	global_load_lds_dwordx4 v[220:221], off
	v_lshl_add_u64 v[220:221], s[52:53], 0, v[152:153]
	s_add_i32 m0, s54, 0x2000
	s_nop 0
	global_load_lds_dwordx4 v[220:221], off
	s_mov_b32 m0, s62
	s_nop 0
	global_load_lds_dwordx4 v[216:217], off
	v_lshl_add_u64 v[216:217], v[218:219], 0, s[12:13]
	s_mov_b32 m0, s63
	s_nop 0
	global_load_lds_dwordx4 v[216:217], off
	s_add_i32 s69, s69, 2
	s_add_u32 s30, s30, 0x10000
	s_addc_u32 s31, s31, 0
	s_add_u32 s44, s44, 0x100
	s_addc_u32 s45, s45, 0
	s_cmp_gt_u32 s69, 29
	s_waitcnt vmcnt(8)
	s_waitcnt lgkmcnt(0)
	s_barrier
	s_setprio 1
	s_waitcnt lgkmcnt(0)
	v_mfma_f32_16x16x32_bf16 v[62:65], v[130:133], v[184:187], v[62:65]
	v_mfma_f32_16x16x32_bf16 v[58:61], v[138:141], v[184:187], v[58:61]
	v_mfma_f32_16x16x32_bf16 v[46:49], v[130:133], v[192:195], v[46:49]
	v_mfma_f32_16x16x32_bf16 v[42:45], v[138:141], v[192:195], v[42:45]
	v_mfma_f32_16x16x32_bf16 v[30:33], v[130:133], v[200:203], v[30:33]
	v_mfma_f32_16x16x32_bf16 v[26:29], v[138:141], v[200:203], v[26:29]
	v_mfma_f32_16x16x32_bf16 v[14:17], v[130:133], v[208:211], v[14:17]
	v_mfma_f32_16x16x32_bf16 v[10:13], v[138:141], v[208:211], v[10:13]
	v_mfma_f32_16x16x32_bf16 v[62:65], v[134:137], v[188:191], v[62:65]
	v_mfma_f32_16x16x32_bf16 v[58:61], v[142:145], v[188:191], v[58:61]
	v_mfma_f32_16x16x32_bf16 v[46:49], v[134:137], v[196:199], v[46:49]
	v_mfma_f32_16x16x32_bf16 v[42:45], v[142:145], v[196:199], v[42:45]
	v_mfma_f32_16x16x32_bf16 v[30:33], v[134:137], v[204:207], v[30:33]
	v_mfma_f32_16x16x32_bf16 v[26:29], v[142:145], v[204:207], v[26:29]
	v_mfma_f32_16x16x32_bf16 v[14:17], v[134:137], v[212:215], v[14:17]
	v_mfma_f32_16x16x32_bf16 v[10:13], v[142:145], v[212:215], v[10:13]
	s_setprio 0
	s_setprio 1
	v_mfma_f32_16x16x32_bf16 v[54:57], v[162:165], v[184:187], v[54:57]
	v_mfma_f32_16x16x32_bf16 v[50:53], v[176:179], v[184:187], v[50:53]
	v_mfma_f32_16x16x32_bf16 v[38:41], v[162:165], v[192:195], v[38:41]
	v_mfma_f32_16x16x32_bf16 v[34:37], v[176:179], v[192:195], v[34:37]
	v_mfma_f32_16x16x32_bf16 v[22:25], v[162:165], v[200:203], v[22:25]
	v_mfma_f32_16x16x32_bf16 v[18:21], v[176:179], v[200:203], v[18:21]
	v_mfma_f32_16x16x32_bf16 v[6:9], v[162:165], v[208:211], v[6:9]
	v_mfma_f32_16x16x32_bf16 v[2:5], v[176:179], v[208:211], v[2:5]
	v_mfma_f32_16x16x32_bf16 v[54:57], v[166:169], v[188:191], v[54:57]
	v_mfma_f32_16x16x32_bf16 v[50:53], v[180:183], v[188:191], v[50:53]
	v_mfma_f32_16x16x32_bf16 v[38:41], v[166:169], v[196:199], v[38:41]
	v_mfma_f32_16x16x32_bf16 v[34:37], v[180:183], v[196:199], v[34:37]
	v_mfma_f32_16x16x32_bf16 v[22:25], v[166:169], v[204:207], v[22:25]
	v_mfma_f32_16x16x32_bf16 v[18:21], v[180:183], v[204:207], v[18:21]
	v_mfma_f32_16x16x32_bf16 v[6:9], v[166:169], v[212:215], v[6:9]
	v_mfma_f32_16x16x32_bf16 v[2:5], v[180:183], v[212:215], v[2:5]
	s_setprio 0
	s_barrier
	s_cbranch_scc1 .Lmy_rot8_exit
	ds_read_b128 v[130:133], v173
	ds_read_b128 v[134:137], v173 offset:1024
	ds_read_b128 v[138:141], v173 offset:2048
	ds_read_b128 v[142:145], v173 offset:3072
	ds_read_b128 v[162:165], v174
	ds_read_b128 v[166:169], v174 offset:1024
	ds_read_b128 v[176:179], v174 offset:2048
	ds_read_b128 v[180:183], v174 offset:3072
	s_branch .Lmy_rot8_head

.Lmy_rot10_head:
	s_add_u32 s24, s22, 0xfff80080
	s_addc_u32 s25, s23, -1
	s_cmp_eq_u32 s59, 28
	s_cselect_b32 s27, s15, s25
	s_cselect_b32 s26, s58, s24
	s_cselect_b32 s25, s13, s31
	s_cselect_b32 s24, s33, s30
	v_lshl_add_u64 v[220:221], s[22:23], 0, v[140:141]
	s_add_i32 m0, s37, 0xc000
	ds_read_b128 v[188:191], v154
	ds_read_b128 v[192:195], v154 offset:1024
	ds_read_b128 v[196:199], v154 offset:2048
	ds_read_b128 v[200:203], v154 offset:3072
	ds_read_b128 v[204:207], v154 offset:4096
	ds_read_b128 v[208:211], v154 offset:5120
	ds_read_b128 v[212:215], v154 offset:6144
	ds_read_b128 v[216:219], v154 offset:7168
	global_load_lds_dwordx4 v[220:221], off
	v_lshl_add_u64 v[220:221], s[22:23], 0, v[142:143]
	s_add_i32 m0, s37, 0xe000
	s_nop 0
	global_load_lds_dwordx4 v[220:221], off
	s_waitcnt vmcnt(8)
	s_waitcnt lgkmcnt(0)
	s_barrier
	s_setprio 1
	s_waitcnt lgkmcnt(0)
	v_mfma_f32_16x16x32_bf16 v[126:129], v[156:159], v[188:191], v[126:129]
	v_mfma_f32_16x16x32_bf16 v[122:125], v[164:167], v[188:191], v[122:125]
	v_mfma_f32_16x16x32_bf16 v[110:113], v[156:159], v[196:199], v[110:113]
	v_mfma_f32_16x16x32_bf16 v[106:109], v[164:167], v[196:199], v[106:109]
	v_mfma_f32_16x16x32_bf16 v[94:97], v[156:159], v[204:207], v[94:97]
	v_mfma_f32_16x16x32_bf16 v[90:93], v[164:167], v[204:207], v[90:93]
	v_mfma_f32_16x16x32_bf16 v[78:81], v[156:159], v[212:215], v[78:81]
	v_mfma_f32_16x16x32_bf16 v[74:77], v[164:167], v[212:215], v[74:77]
	v_mfma_f32_16x16x32_bf16 v[126:129], v[160:163], v[192:195], v[126:129]
	v_mfma_f32_16x16x32_bf16 v[122:125], v[168:171], v[192:195], v[122:125]
	v_mfma_f32_16x16x32_bf16 v[110:113], v[160:163], v[200:203], v[110:113]
	v_mfma_f32_16x16x32_bf16 v[106:109], v[168:171], v[200:203], v[106:109]
	v_mfma_f32_16x16x32_bf16 v[94:97], v[160:163], v[208:211], v[94:97]
	v_mfma_f32_16x16x32_bf16 v[90:93], v[168:171], v[208:211], v[90:93]
	v_mfma_f32_16x16x32_bf16 v[78:81], v[160:163], v[216:219], v[78:81]
	v_mfma_f32_16x16x32_bf16 v[74:77], v[168:171], v[216:219], v[74:77]
	s_setprio 0
	s_setprio 1
	v_mfma_f32_16x16x32_bf16 v[118:121], v[172:175], v[188:191], v[118:121]
	v_mfma_f32_16x16x32_bf16 v[114:117], v[180:183], v[188:191], v[114:117]
	v_mfma_f32_16x16x32_bf16 v[102:105], v[172:175], v[196:199], v[102:105]
	v_mfma_f32_16x16x32_bf16 v[98:101], v[180:183], v[196:199], v[98:101]
	v_mfma_f32_16x16x32_bf16 v[86:89], v[172:175], v[204:207], v[86:89]
	v_mfma_f32_16x16x32_bf16 v[82:85], v[180:183], v[204:207], v[82:85]
	v_mfma_f32_16x16x32_bf16 v[70:73], v[172:175], v[212:215], v[70:73]
	v_mfma_f32_16x16x32_bf16 v[66:69], v[180:183], v[212:215], v[66:69]
	v_mfma_f32_16x16x32_bf16 v[118:121], v[176:179], v[192:195], v[118:121]
	v_mfma_f32_16x16x32_bf16 v[114:117], v[184:187], v[192:195], v[114:117]
	v_mfma_f32_16x16x32_bf16 v[102:105], v[176:179], v[200:203], v[102:105]
	v_mfma_f32_16x16x32_bf16 v[98:101], v[184:187], v[200:203], v[98:101]
	v_mfma_f32_16x16x32_bf16 v[86:89], v[176:179], v[208:211], v[86:89]
	v_mfma_f32_16x16x32_bf16 v[82:85], v[184:187], v[208:211], v[82:85]
	v_mfma_f32_16x16x32_bf16 v[70:73], v[176:179], v[216:219], v[70:73]
	v_mfma_f32_16x16x32_bf16 v[66:69], v[184:187], v[216:219], v[66:69]
	s_setprio 0
	s_barrier
	s_add_i32 s60, s55, s34
	v_lshl_add_u64 v[220:221], s[24:25], 0, v[134:135]
	s_mov_b32 m0, s60
	ds_read_b128 v[188:191], v154 offset:16384
	ds_read_b128 v[192:195], v154 offset:17408
	ds_read_b128 v[196:199], v154 offset:18432
	ds_read_b128 v[200:203], v154 offset:19456
	ds_read_b128 v[204:207], v154 offset:20480
	ds_read_b128 v[208:211], v154 offset:21504
	ds_read_b128 v[212:215], v154 offset:22528
	ds_read_b128 v[216:219], v154 offset:23552
	global_load_lds_dwordx4 v[220:221], off
	s_add_i32 m0, s60, 0x2000
	s_add_u32 s60, s24, 0x4000
	v_lshl_add_u64 v[220:221], s[24:25], 0, v[130:131]
	s_addc_u32 s61, s25, 0
	s_add_i32 s62, s56, s34
	global_load_lds_dwordx4 v[220:221], off
	v_lshl_add_u64 v[220:221], s[60:61], 0, v[134:135]
	s_mov_b32 m0, s62
	v_lshl_add_u64 v[222:223], s[26:27], 0, v[132:133]
	global_load_lds_dwordx4 v[220:221], off
	v_lshl_add_u64 v[220:221], s[60:61], 0, v[130:131]
	s_add_i32 m0, s62, 0x2000
	s_nop 0
	global_load_lds_dwordx4 v[220:221], off
	v_lshl_add_u64 v[220:221], s[26:27], 0, v[136:137]
	s_mov_b32 m0, s37
	s_nop 0
	global_load_lds_dwordx4 v[220:221], off
	s_mov_b32 m0, s40
	s_nop 0
	global_load_lds_dwordx4 v[222:223], off
	s_waitcnt vmcnt(8)
	s_waitcnt lgkmcnt(0)
	s_barrier
	s_setprio 1
	s_waitcnt lgkmcnt(0)
	v_mfma_f32_16x16x32_bf16 v[62:65], v[156:159], v[188:191], v[62:65]
	v_mfma_f32_16x16x32_bf16 v[58:61], v[164:167], v[188:191], v[58:61]
	v_mfma_f32_16x16x32_bf16 v[46:49], v[156:159], v[196:199], v[46:49]
	v_mfma_f32_16x16x32_bf16 v[42:45], v[164:167], v[196:199], v[42:45]
	v_mfma_f32_16x16x32_bf16 v[30:33], v[156:159], v[204:207], v[30:33]
	v_mfma_f32_16x16x32_bf16 v[26:29], v[164:167], v[204:207], v[26:29]
	v_mfma_f32_16x16x32_bf16 v[14:17], v[156:159], v[212:215], v[14:17]
	v_mfma_f32_16x16x32_bf16 v[10:13], v[164:167], v[212:215], v[10:13]
	v_mfma_f32_16x16x32_bf16 v[62:65], v[160:163], v[192:195], v[62:65]
	v_mfma_f32_16x16x32_bf16 v[58:61], v[168:171], v[192:195], v[58:61]
	v_mfma_f32_16x16x32_bf16 v[46:49], v[160:163], v[200:203], v[46:49]
	v_mfma_f32_16x16x32_bf16 v[42:45], v[168:171], v[200:203], v[42:45]
	v_mfma_f32_16x16x32_bf16 v[30:33], v[160:163], v[208:211], v[30:33]
	v_mfma_f32_16x16x32_bf16 v[26:29], v[168:171], v[208:211], v[26:29]
	v_mfma_f32_16x16x32_bf16 v[14:17], v[160:163], v[216:219], v[14:17]
	v_mfma_f32_16x16x32_bf16 v[10:13], v[168:171], v[216:219], v[10:13]
	s_setprio 0
	s_setprio 1
	v_mfma_f32_16x16x32_bf16 v[54:57], v[172:175], v[188:191], v[54:57]
	v_mfma_f32_16x16x32_bf16 v[50:53], v[180:183], v[188:191], v[50:53]
	v_mfma_f32_16x16x32_bf16 v[38:41], v[172:175], v[196:199], v[38:41]
	v_mfma_f32_16x16x32_bf16 v[34:37], v[180:183], v[196:199], v[34:37]
	v_mfma_f32_16x16x32_bf16 v[22:25], v[172:175], v[204:207], v[22:25]
	v_mfma_f32_16x16x32_bf16 v[18:21], v[180:183], v[204:207], v[18:21]
	v_mfma_f32_16x16x32_bf16 v[6:9], v[172:175], v[212:215], v[6:9]
	v_mfma_f32_16x16x32_bf16 v[2:5], v[180:183], v[212:215], v[2:5]
	v_mfma_f32_16x16x32_bf16 v[54:57], v[176:179], v[192:195], v[54:57]
	v_mfma_f32_16x16x32_bf16 v[50:53], v[184:187], v[192:195], v[50:53]
	v_mfma_f32_16x16x32_bf16 v[38:41], v[176:179], v[200:203], v[38:41]
	v_mfma_f32_16x16x32_bf16 v[34:37], v[184:187], v[200:203], v[34:37]
	v_mfma_f32_16x16x32_bf16 v[22:25], v[176:179], v[208:211], v[22:25]
	v_mfma_f32_16x16x32_bf16 v[18:21], v[184:187], v[208:211], v[18:21]
	v_mfma_f32_16x16x32_bf16 v[6:9], v[176:179], v[216:219], v[6:9]
	v_mfma_f32_16x16x32_bf16 v[2:5], v[184:187], v[216:219], v[2:5]
	s_setprio 0
	s_barrier
	s_add_i32 s60, 0, 0x18000
	v_add_u32_e32 v138, s60, v151
	s_add_i32 s61, 0, 0x1c000
	ds_read_b128 v[156:159], v138
	ds_read_b128 v[160:163], v138 offset:1024
	ds_read_b128 v[164:167], v138 offset:2048
	ds_read_b128 v[168:171], v138 offset:3072
	v_add_u32_e32 v138, s61, v151
	ds_read_b128 v[172:175], v138
	ds_read_b128 v[176:179], v138 offset:1024
	ds_read_b128 v[180:183], v138 offset:2048
	ds_read_b128 v[184:187], v138 offset:3072
	s_add_u32 s26, s26, 0x80000
	s_addc_u32 s27, s27, 0
	s_mov_b32 m0, s41
	v_lshl_add_u64 v[224:225], s[26:27], 0, v[136:137]
	ds_read_b128 v[188:191], v154 offset:32768
	ds_read_b128 v[192:195], v154 offset:33792
	ds_read_b128 v[196:199], v154 offset:34816
	ds_read_b128 v[200:203], v154 offset:35840
	ds_read_b128 v[204:207], v154 offset:36864
	ds_read_b128 v[208:211], v154 offset:37888
	ds_read_b128 v[212:215], v154 offset:38912
	ds_read_b128 v[216:219], v154 offset:39936
	global_load_lds_dwordx4 v[224:225], off
	v_lshl_add_u64 v[224:225], s[26:27], 0, v[132:133]
	s_mov_b32 m0, s42
	s_nop 0
	global_load_lds_dwordx4 v[224:225], off
	s_waitcnt vmcnt(8)
	s_waitcnt lgkmcnt(0)
	s_barrier
	s_setprio 1
	s_waitcnt lgkmcnt(0)
	v_mfma_f32_16x16x32_bf16 v[126:129], v[156:159], v[188:191], v[126:129]
	v_mfma_f32_16x16x32_bf16 v[122:125], v[164:167], v[188:191], v[122:125]
	v_mfma_f32_16x16x32_bf16 v[110:113], v[156:159], v[196:199], v[110:113]
	v_mfma_f32_16x16x32_bf16 v[106:109], v[164:167], v[196:199], v[106:109]
	v_mfma_f32_16x16x32_bf16 v[94:97], v[156:159], v[204:207], v[94:97]
	v_mfma_f32_16x16x32_bf16 v[90:93], v[164:167], v[204:207], v[90:93]
	v_mfma_f32_16x16x32_bf16 v[78:81], v[156:159], v[212:215], v[78:81]
	v_mfma_f32_16x16x32_bf16 v[74:77], v[164:167], v[212:215], v[74:77]
	v_mfma_f32_16x16x32_bf16 v[126:129], v[160:163], v[192:195], v[126:129]
	v_mfma_f32_16x16x32_bf16 v[122:125], v[168:171], v[192:195], v[122:125]
	v_mfma_f32_16x16x32_bf16 v[110:113], v[160:163], v[200:203], v[110:113]
	v_mfma_f32_16x16x32_bf16 v[106:109], v[168:171], v[200:203], v[106:109]
	v_mfma_f32_16x16x32_bf16 v[94:97], v[160:163], v[208:211], v[94:97]
	v_mfma_f32_16x16x32_bf16 v[90:93], v[168:171], v[208:211], v[90:93]
	v_mfma_f32_16x16x32_bf16 v[78:81], v[160:163], v[216:219], v[78:81]
	v_mfma_f32_16x16x32_bf16 v[74:77], v[168:171], v[216:219], v[74:77]
	s_setprio 0
	s_setprio 1
	v_mfma_f32_16x16x32_bf16 v[118:121], v[172:175], v[188:191], v[118:121]
	v_mfma_f32_16x16x32_bf16 v[114:117], v[180:183], v[188:191], v[114:117]
	v_mfma_f32_16x16x32_bf16 v[102:105], v[172:175], v[196:199], v[102:105]
	v_mfma_f32_16x16x32_bf16 v[98:101], v[180:183], v[196:199], v[98:101]
	v_mfma_f32_16x16x32_bf16 v[86:89], v[172:175], v[204:207], v[86:89]
	v_mfma_f32_16x16x32_bf16 v[82:85], v[180:183], v[204:207], v[82:85]
	v_mfma_f32_16x16x32_bf16 v[70:73], v[172:175], v[212:215], v[70:73]
	v_mfma_f32_16x16x32_bf16 v[66:69], v[180:183], v[212:215], v[66:69]
	v_mfma_f32_16x16x32_bf16 v[118:121], v[176:179], v[192:195], v[118:121]
	v_mfma_f32_16x16x32_bf16 v[114:117], v[184:187], v[192:195], v[114:117]
	v_mfma_f32_16x16x32_bf16 v[102:105], v[176:179], v[200:203], v[102:105]
	v_mfma_f32_16x16x32_bf16 v[98:101], v[184:187], v[200:203], v[98:101]
	v_mfma_f32_16x16x32_bf16 v[86:89], v[176:179], v[208:211], v[86:89]
	v_mfma_f32_16x16x32_bf16 v[82:85], v[184:187], v[208:211], v[82:85]
	v_mfma_f32_16x16x32_bf16 v[70:73], v[176:179], v[216:219], v[70:73]
	v_mfma_f32_16x16x32_bf16 v[66:69], v[184:187], v[216:219], v[66:69]
	s_setprio 0
	s_barrier
	s_add_u32 s26, s24, 0x8000
	s_addc_u32 s27, s25, 0
	s_add_i32 s60, s60, s34
	v_lshl_add_u64 v[224:225], s[26:27], 0, v[134:135]
	s_mov_b32 m0, s60
	ds_read_b128 v[188:191], v154 offset:49152
	ds_read_b128 v[192:195], v154 offset:50176
	ds_read_b128 v[196:199], v154 offset:51200
	ds_read_b128 v[200:203], v154 offset:52224
	ds_read_b128 v[204:207], v154 offset:53248
	ds_read_b128 v[208:211], v154 offset:54272
	ds_read_b128 v[212:215], v154 offset:55296
	ds_read_b128 v[216:219], v154 offset:56320
	global_load_lds_dwordx4 v[224:225], off
	s_add_i32 m0, s60, 0x2000
	s_add_u32 s24, s24, 0xc000
	v_lshl_add_u64 v[224:225], s[26:27], 0, v[130:131]
	s_addc_u32 s25, s25, 0
	s_add_i32 s26, s61, s34
	global_load_lds_dwordx4 v[224:225], off
	v_lshl_add_u64 v[224:225], s[24:25], 0, v[134:135]
	s_mov_b32 m0, s26
	v_lshl_add_u64 v[220:221], v[220:221], 0, s[8:9]
	global_load_lds_dwordx4 v[224:225], off
	v_lshl_add_u64 v[224:225], s[24:25], 0, v[130:131]
	s_add_i32 m0, s26, 0x2000
	s_nop 0
	global_load_lds_dwordx4 v[224:225], off
	s_mov_b32 m0, s52
	s_nop 0
	global_load_lds_dwordx4 v[220:221], off
	v_lshl_add_u64 v[220:221], v[222:223], 0, s[8:9]
	s_mov_b32 m0, s53
	s_nop 0
	global_load_lds_dwordx4 v[220:221], off
	s_add_i32 s59, s59, 2
	s_add_u32 s30, s30, 0x10000
	s_addc_u32 s31, s31, 0
	s_add_u32 s22, s22, 0x100
	s_addc_u32 s23, s23, 0
	s_cmp_gt_u32 s59, 29
	s_waitcnt vmcnt(8)
	s_waitcnt lgkmcnt(0)
	s_barrier
	s_setprio 1
	s_waitcnt lgkmcnt(0)
	v_mfma_f32_16x16x32_bf16 v[62:65], v[156:159], v[188:191], v[62:65]
	v_mfma_f32_16x16x32_bf16 v[58:61], v[164:167], v[188:191], v[58:61]
	v_mfma_f32_16x16x32_bf16 v[46:49], v[156:159], v[196:199], v[46:49]
	v_mfma_f32_16x16x32_bf16 v[42:45], v[164:167], v[196:199], v[42:45]
	v_mfma_f32_16x16x32_bf16 v[30:33], v[156:159], v[204:207], v[30:33]
	v_mfma_f32_16x16x32_bf16 v[26:29], v[164:167], v[204:207], v[26:29]
	v_mfma_f32_16x16x32_bf16 v[14:17], v[156:159], v[212:215], v[14:17]
	v_mfma_f32_16x16x32_bf16 v[10:13], v[164:167], v[212:215], v[10:13]
	v_mfma_f32_16x16x32_bf16 v[62:65], v[160:163], v[192:195], v[62:65]
	v_mfma_f32_16x16x32_bf16 v[58:61], v[168:171], v[192:195], v[58:61]
	v_mfma_f32_16x16x32_bf16 v[46:49], v[160:163], v[200:203], v[46:49]
	v_mfma_f32_16x16x32_bf16 v[42:45], v[168:171], v[200:203], v[42:45]
	v_mfma_f32_16x16x32_bf16 v[30:33], v[160:163], v[208:211], v[30:33]
	v_mfma_f32_16x16x32_bf16 v[26:29], v[168:171], v[208:211], v[26:29]
	v_mfma_f32_16x16x32_bf16 v[14:17], v[160:163], v[216:219], v[14:17]
	v_mfma_f32_16x16x32_bf16 v[10:13], v[168:171], v[216:219], v[10:13]
	s_setprio 0
	s_setprio 1
	v_mfma_f32_16x16x32_bf16 v[54:57], v[172:175], v[188:191], v[54:57]
	v_mfma_f32_16x16x32_bf16 v[50:53], v[180:183], v[188:191], v[50:53]
	v_mfma_f32_16x16x32_bf16 v[38:41], v[172:175], v[196:199], v[38:41]
	v_mfma_f32_16x16x32_bf16 v[34:37], v[180:183], v[196:199], v[34:37]
	v_mfma_f32_16x16x32_bf16 v[22:25], v[172:175], v[204:207], v[22:25]
	v_mfma_f32_16x16x32_bf16 v[18:21], v[180:183], v[204:207], v[18:21]
	v_mfma_f32_16x16x32_bf16 v[6:9], v[172:175], v[212:215], v[6:9]
	v_mfma_f32_16x16x32_bf16 v[2:5], v[180:183], v[212:215], v[2:5]
	v_mfma_f32_16x16x32_bf16 v[54:57], v[176:179], v[192:195], v[54:57]
	v_mfma_f32_16x16x32_bf16 v[50:53], v[184:187], v[192:195], v[50:53]
	v_mfma_f32_16x16x32_bf16 v[38:41], v[176:179], v[200:203], v[38:41]
	v_mfma_f32_16x16x32_bf16 v[34:37], v[184:187], v[200:203], v[34:37]
	v_mfma_f32_16x16x32_bf16 v[22:25], v[176:179], v[208:211], v[22:25]
	v_mfma_f32_16x16x32_bf16 v[18:21], v[184:187], v[208:211], v[18:21]
	v_mfma_f32_16x16x32_bf16 v[6:9], v[176:179], v[216:219], v[6:9]
	v_mfma_f32_16x16x32_bf16 v[2:5], v[184:187], v[216:219], v[2:5]
	s_setprio 0
	s_barrier
	s_cbranch_scc1 .Lmy_rot10_exit
	ds_read_b128 v[156:159], v152
	ds_read_b128 v[160:163], v152 offset:1024
	ds_read_b128 v[164:167], v152 offset:2048
	ds_read_b128 v[168:171], v152 offset:3072
	ds_read_b128 v[172:175], v153
	ds_read_b128 v[176:179], v153 offset:1024
	ds_read_b128 v[180:183], v153 offset:2048
	ds_read_b128 v[184:187], v153 offset:3072
	s_branch .Lmy_rot10_head
.Lmy_rot10_exit:
	s_and_b64 vcc, exec, s[10:11]
	s_cbranch_vccz .LBB0_989
	s_barrier

.Lmy_rot11_head:
	s_add_u32 s16, s14, 0x4000
	s_addc_u32 s17, s15, 0
	s_cmpk_eq_i32 s47, 0x54
	s_cselect_b32 s20, s4, s16
	s_cselect_b32 s21, s5, s17
	s_cselect_b32 s18, s12, s45
	s_cselect_b32 s19, s13, s46
	s_add_u32 s16, s20, 0x8000
	s_addc_u32 s17, s21, 0
	v_lshl_add_u64 v[214:215], s[14:15], 0, v[136:137]
	s_add_i32 m0, s26, 0xc000
	ds_read_b128 v[182:185], v173
	ds_read_b128 v[186:189], v173 offset:1024
	ds_read_b128 v[190:193], v173 offset:2048
	ds_read_b128 v[194:197], v173 offset:3072
	ds_read_b128 v[198:201], v173 offset:4096
	ds_read_b128 v[202:205], v173 offset:5120
	ds_read_b128 v[206:209], v173 offset:6144
	ds_read_b128 v[210:213], v173 offset:7168
	global_load_lds_dwordx4 v[214:215], off
	v_lshl_add_u64 v[214:215], s[14:15], 0, v[138:139]
	s_add_i32 m0, s26, 0xe000
	s_nop 0
	global_load_lds_dwordx4 v[214:215], off
	s_waitcnt vmcnt(8)
	s_waitcnt lgkmcnt(0)
	s_barrier
	s_setprio 1
	s_waitcnt lgkmcnt(0)
	v_mfma_f32_16x16x32_bf16 v[124:127], v[144:147], v[182:185], v[124:127]
	v_mfma_f32_16x16x32_bf16 v[120:123], v[152:155], v[182:185], v[120:123]
	v_mfma_f32_16x16x32_bf16 v[116:119], v[144:147], v[190:193], v[116:119]
	v_mfma_f32_16x16x32_bf16 v[112:115], v[152:155], v[190:193], v[112:115]
	v_mfma_f32_16x16x32_bf16 v[92:95], v[144:147], v[198:201], v[92:95]
	v_mfma_f32_16x16x32_bf16 v[88:91], v[152:155], v[198:201], v[88:91]
	v_mfma_f32_16x16x32_bf16 v[76:79], v[144:147], v[206:209], v[76:79]
	v_mfma_f32_16x16x32_bf16 v[72:75], v[152:155], v[206:209], v[72:75]
	v_mfma_f32_16x16x32_bf16 v[124:127], v[148:151], v[186:189], v[124:127]
	v_mfma_f32_16x16x32_bf16 v[120:123], v[156:159], v[186:189], v[120:123]
	v_mfma_f32_16x16x32_bf16 v[116:119], v[148:151], v[194:197], v[116:119]
	v_mfma_f32_16x16x32_bf16 v[112:115], v[156:159], v[194:197], v[112:115]
	v_mfma_f32_16x16x32_bf16 v[92:95], v[148:151], v[202:205], v[92:95]
	v_mfma_f32_16x16x32_bf16 v[88:91], v[156:159], v[202:205], v[88:91]
	v_mfma_f32_16x16x32_bf16 v[76:79], v[148:151], v[210:213], v[76:79]
	v_mfma_f32_16x16x32_bf16 v[72:75], v[156:159], v[210:213], v[72:75]
	s_setprio 0
	s_setprio 1
	v_mfma_f32_16x16x32_bf16 v[108:111], v[160:163], v[182:185], v[108:111]
	v_mfma_f32_16x16x32_bf16 v[104:107], v[174:177], v[182:185], v[104:107]
	v_mfma_f32_16x16x32_bf16 v[100:103], v[160:163], v[190:193], v[100:103]
	v_mfma_f32_16x16x32_bf16 v[96:99], v[174:177], v[190:193], v[96:99]
	v_mfma_f32_16x16x32_bf16 v[84:87], v[160:163], v[198:201], v[84:87]
	v_mfma_f32_16x16x32_bf16 v[80:83], v[174:177], v[198:201], v[80:83]
	v_mfma_f32_16x16x32_bf16 v[68:71], v[160:163], v[206:209], v[68:71]
	v_mfma_f32_16x16x32_bf16 v[64:67], v[174:177], v[206:209], v[64:67]
	v_mfma_f32_16x16x32_bf16 v[108:111], v[164:167], v[186:189], v[108:111]
	v_mfma_f32_16x16x32_bf16 v[104:107], v[178:181], v[186:189], v[104:107]
	v_mfma_f32_16x16x32_bf16 v[100:103], v[164:167], v[194:197], v[100:103]
	v_mfma_f32_16x16x32_bf16 v[96:99], v[178:181], v[194:197], v[96:99]
	v_mfma_f32_16x16x32_bf16 v[84:87], v[164:167], v[202:205], v[84:87]
	v_mfma_f32_16x16x32_bf16 v[80:83], v[178:181], v[202:205], v[80:83]
	v_mfma_f32_16x16x32_bf16 v[68:71], v[164:167], v[210:213], v[68:71]
	v_mfma_f32_16x16x32_bf16 v[64:67], v[178:181], v[210:213], v[64:67]
	s_setprio 0
	s_barrier
	s_add_i32 s50, s37, s25
	v_lshl_add_u64 v[214:215], s[18:19], 0, v[130:131]
	s_mov_b32 m0, s50
	ds_read_b128 v[182:185], v173 offset:16384
	ds_read_b128 v[186:189], v173 offset:17408
	ds_read_b128 v[190:193], v173 offset:18432
	ds_read_b128 v[194:197], v173 offset:19456
	ds_read_b128 v[198:201], v173 offset:20480
	ds_read_b128 v[202:205], v173 offset:21504
	ds_read_b128 v[206:209], v173 offset:22528
	ds_read_b128 v[210:213], v173 offset:23552
	global_load_lds_dwordx4 v[214:215], off
	s_add_i32 m0, s50, 0x2000
	s_add_u32 s50, s18, 0x4000
	v_lshl_add_u64 v[214:215], s[18:19], 0, v[134:135]
	s_addc_u32 s51, s19, 0
	s_add_i32 s52, s40, s25
	global_load_lds_dwordx4 v[214:215], off
	v_lshl_add_u64 v[214:215], s[50:51], 0, v[130:131]
	s_mov_b32 m0, s52
	s_nop 0
	global_load_lds_dwordx4 v[214:215], off
	v_lshl_add_u64 v[214:215], s[50:51], 0, v[134:135]
	s_add_i32 m0, s52, 0x2000
	s_nop 0
	global_load_lds_dwordx4 v[214:215], off
	v_lshl_add_u64 v[214:215], s[20:21], 0, v[128:129]
	s_mov_b32 m0, s26
	s_nop 0
	global_load_lds_dwordx4 v[214:215], off
	v_lshl_add_u64 v[214:215], s[20:21], 0, v[132:133]
	s_mov_b32 m0, s27
	s_nop 0
	global_load_lds_dwordx4 v[214:215], off
	s_waitcnt vmcnt(8)
	s_waitcnt lgkmcnt(0)
	s_barrier
	s_setprio 1
	s_waitcnt lgkmcnt(0)
	v_mfma_f32_16x16x32_bf16 v[60:63], v[144:147], v[182:185], v[60:63]
	v_mfma_f32_16x16x32_bf16 v[56:59], v[152:155], v[182:185], v[56:59]
	v_mfma_f32_16x16x32_bf16 v[44:47], v[144:147], v[190:193], v[44:47]
	v_mfma_f32_16x16x32_bf16 v[40:43], v[152:155], v[190:193], v[40:43]
	v_mfma_f32_16x16x32_bf16 v[28:31], v[144:147], v[198:201], v[28:31]
	v_mfma_f32_16x16x32_bf16 v[24:27], v[152:155], v[198:201], v[24:27]
	v_mfma_f32_16x16x32_bf16 v[12:15], v[144:147], v[206:209], v[12:15]
	v_mfma_f32_16x16x32_bf16 v[8:11], v[152:155], v[206:209], v[8:11]
	v_mfma_f32_16x16x32_bf16 v[60:63], v[148:151], v[186:189], v[60:63]
	v_mfma_f32_16x16x32_bf16 v[56:59], v[156:159], v[186:189], v[56:59]
	v_mfma_f32_16x16x32_bf16 v[44:47], v[148:151], v[194:197], v[44:47]
	v_mfma_f32_16x16x32_bf16 v[40:43], v[156:159], v[194:197], v[40:43]
	v_mfma_f32_16x16x32_bf16 v[28:31], v[148:151], v[202:205], v[28:31]
	v_mfma_f32_16x16x32_bf16 v[24:27], v[156:159], v[202:205], v[24:27]
	v_mfma_f32_16x16x32_bf16 v[12:15], v[148:151], v[210:213], v[12:15]
	v_mfma_f32_16x16x32_bf16 v[8:11], v[156:159], v[210:213], v[8:11]
	s_setprio 0
	s_setprio 1
	v_mfma_f32_16x16x32_bf16 v[52:55], v[160:163], v[182:185], v[52:55]
	v_mfma_f32_16x16x32_bf16 v[48:51], v[174:177], v[182:185], v[48:51]
	v_mfma_f32_16x16x32_bf16 v[36:39], v[160:163], v[190:193], v[36:39]
	v_mfma_f32_16x16x32_bf16 v[32:35], v[174:177], v[190:193], v[32:35]
	v_mfma_f32_16x16x32_bf16 v[20:23], v[160:163], v[198:201], v[20:23]
	v_mfma_f32_16x16x32_bf16 v[16:19], v[174:177], v[198:201], v[16:19]
	v_mfma_f32_16x16x32_bf16 v[4:7], v[160:163], v[206:209], v[4:7]
	v_mfma_f32_16x16x32_bf16 v[0:3], v[174:177], v[206:209], v[0:3]
	v_mfma_f32_16x16x32_bf16 v[52:55], v[164:167], v[186:189], v[52:55]
	v_mfma_f32_16x16x32_bf16 v[48:51], v[178:181], v[186:189], v[48:51]
	v_mfma_f32_16x16x32_bf16 v[36:39], v[164:167], v[194:197], v[36:39]
	v_mfma_f32_16x16x32_bf16 v[32:35], v[178:181], v[194:197], v[32:35]
	v_mfma_f32_16x16x32_bf16 v[20:23], v[164:167], v[202:205], v[20:23]
	v_mfma_f32_16x16x32_bf16 v[16:19], v[178:181], v[202:205], v[16:19]
	v_mfma_f32_16x16x32_bf16 v[4:7], v[164:167], v[210:213], v[4:7]
	v_mfma_f32_16x16x32_bf16 v[0:3], v[178:181], v[210:213], v[0:3]
	s_setprio 0
	s_barrier
	s_add_i32 s50, 0, 0x18000
	s_add_i32 s51, 0, 0x1c000
	v_add_u32_e32 v156, s50, v169
	v_add_u32_e32 v178, s51, v169
	ds_read_b128 v[144:147], v156
	ds_read_b128 v[148:151], v156 offset:1024
	ds_read_b128 v[152:155], v156 offset:2048
	ds_read_b128 v[156:159], v156 offset:3072
	ds_read_b128 v[160:163], v178
	ds_read_b128 v[164:167], v178 offset:1024
	ds_read_b128 v[174:177], v178 offset:2048
	ds_read_b128 v[178:181], v178 offset:3072
	s_add_u32 s20, s20, 0x4000
	s_addc_u32 s21, s21, 0
	s_mov_b32 m0, s28
	v_lshl_add_u64 v[214:215], s[20:21], 0, v[128:129]
	ds_read_b128 v[182:185], v173 offset:32768
	ds_read_b128 v[186:189], v173 offset:33792
	ds_read_b128 v[190:193], v173 offset:34816
	ds_read_b128 v[194:197], v173 offset:35840
	ds_read_b128 v[198:201], v173 offset:36864
	ds_read_b128 v[202:205], v173 offset:37888
	ds_read_b128 v[206:209], v173 offset:38912
	ds_read_b128 v[210:213], v173 offset:39936
	global_load_lds_dwordx4 v[214:215], off
	v_lshl_add_u64 v[214:215], s[20:21], 0, v[132:133]
	s_mov_b32 m0, s29
	s_nop 0
	global_load_lds_dwordx4 v[214:215], off
	s_waitcnt vmcnt(8)
	s_waitcnt lgkmcnt(0)
	s_barrier
	s_setprio 1
	s_waitcnt lgkmcnt(0)
	v_mfma_f32_16x16x32_bf16 v[124:127], v[144:147], v[182:185], v[124:127]
	v_mfma_f32_16x16x32_bf16 v[120:123], v[152:155], v[182:185], v[120:123]
	v_mfma_f32_16x16x32_bf16 v[116:119], v[144:147], v[190:193], v[116:119]
	v_mfma_f32_16x16x32_bf16 v[112:115], v[152:155], v[190:193], v[112:115]
	v_mfma_f32_16x16x32_bf16 v[92:95], v[144:147], v[198:201], v[92:95]
	v_mfma_f32_16x16x32_bf16 v[88:91], v[152:155], v[198:201], v[88:91]
	v_mfma_f32_16x16x32_bf16 v[76:79], v[144:147], v[206:209], v[76:79]
	v_mfma_f32_16x16x32_bf16 v[72:75], v[152:155], v[206:209], v[72:75]
	v_mfma_f32_16x16x32_bf16 v[124:127], v[148:151], v[186:189], v[124:127]
	v_mfma_f32_16x16x32_bf16 v[120:123], v[156:159], v[186:189], v[120:123]
	v_mfma_f32_16x16x32_bf16 v[116:119], v[148:151], v[194:197], v[116:119]
	v_mfma_f32_16x16x32_bf16 v[112:115], v[156:159], v[194:197], v[112:115]
	v_mfma_f32_16x16x32_bf16 v[92:95], v[148:151], v[202:205], v[92:95]
	v_mfma_f32_16x16x32_bf16 v[88:91], v[156:159], v[202:205], v[88:91]
	v_mfma_f32_16x16x32_bf16 v[76:79], v[148:151], v[210:213], v[76:79]
	v_mfma_f32_16x16x32_bf16 v[72:75], v[156:159], v[210:213], v[72:75]
	s_setprio 0
	s_setprio 1
	v_mfma_f32_16x16x32_bf16 v[108:111], v[160:163], v[182:185], v[108:111]
	v_mfma_f32_16x16x32_bf16 v[104:107], v[174:177], v[182:185], v[104:107]
	v_mfma_f32_16x16x32_bf16 v[100:103], v[160:163], v[190:193], v[100:103]
	v_mfma_f32_16x16x32_bf16 v[96:99], v[174:177], v[190:193], v[96:99]
	v_mfma_f32_16x16x32_bf16 v[84:87], v[160:163], v[198:201], v[84:87]
	v_mfma_f32_16x16x32_bf16 v[80:83], v[174:177], v[198:201], v[80:83]
	v_mfma_f32_16x16x32_bf16 v[68:71], v[160:163], v[206:209], v[68:71]
	v_mfma_f32_16x16x32_bf16 v[64:67], v[174:177], v[206:209], v[64:67]
	v_mfma_f32_16x16x32_bf16 v[108:111], v[164:167], v[186:189], v[108:111]
	v_mfma_f32_16x16x32_bf16 v[104:107], v[178:181], v[186:189], v[104:107]
	v_mfma_f32_16x16x32_bf16 v[100:103], v[164:167], v[194:197], v[100:103]
	v_mfma_f32_16x16x32_bf16 v[96:99], v[178:181], v[194:197], v[96:99]
	v_mfma_f32_16x16x32_bf16 v[84:87], v[164:167], v[202:205], v[84:87]
	v_mfma_f32_16x16x32_bf16 v[80:83], v[178:181], v[202:205], v[80:83]
	v_mfma_f32_16x16x32_bf16 v[68:71], v[164:167], v[210:213], v[68:71]
	v_mfma_f32_16x16x32_bf16 v[64:67], v[178:181], v[210:213], v[64:67]
	s_setprio 0
	s_barrier
	s_add_u32 s20, s18, 0x8000
	s_addc_u32 s21, s19, 0
	s_add_i32 s50, s50, s25
	v_lshl_add_u64 v[214:215], s[20:21], 0, v[130:131]
	s_mov_b32 m0, s50
	ds_read_b128 v[182:185], v173 offset:49152
	ds_read_b128 v[186:189], v173 offset:50176
	ds_read_b128 v[190:193], v173 offset:51200
	ds_read_b128 v[194:197], v173 offset:52224
	ds_read_b128 v[198:201], v173 offset:53248
	ds_read_b128 v[202:205], v173 offset:54272
	ds_read_b128 v[206:209], v173 offset:55296
	ds_read_b128 v[210:213], v173 offset:56320
	global_load_lds_dwordx4 v[214:215], off
	s_add_i32 m0, s50, 0x2000
	s_add_u32 s18, s18, 0xc000
	v_lshl_add_u64 v[214:215], s[20:21], 0, v[134:135]
	s_addc_u32 s19, s19, 0
	s_add_i32 s20, s51, s25
	global_load_lds_dwordx4 v[214:215], off
	v_lshl_add_u64 v[214:215], s[18:19], 0, v[130:131]
	s_mov_b32 m0, s20
	s_nop 0
	global_load_lds_dwordx4 v[214:215], off
	v_lshl_add_u64 v[214:215], s[18:19], 0, v[134:135]
	s_add_i32 m0, s20, 0x2000
	s_nop 0
	global_load_lds_dwordx4 v[214:215], off
	v_lshl_add_u64 v[214:215], s[16:17], 0, v[128:129]
	s_mov_b32 m0, s34
	s_nop 0
	global_load_lds_dwordx4 v[214:215], off
	v_lshl_add_u64 v[214:215], s[16:17], 0, v[132:133]
	s_mov_b32 m0, s35
	s_nop 0
	global_load_lds_dwordx4 v[214:215], off
	s_add_i32 s47, s47, 2
	s_add_u32 s14, s14, 0x10000
	s_addc_u32 s15, s15, 0
	s_add_u32 s45, s45, 0x10000
	s_addc_u32 s46, s46, 0
	s_cmpk_gt_u32 s47, 0x55
	s_waitcnt vmcnt(8)
	s_waitcnt lgkmcnt(0)
	s_barrier
	s_setprio 1
	s_waitcnt lgkmcnt(0)
	v_mfma_f32_16x16x32_bf16 v[60:63], v[144:147], v[182:185], v[60:63]
	v_mfma_f32_16x16x32_bf16 v[56:59], v[152:155], v[182:185], v[56:59]
	v_mfma_f32_16x16x32_bf16 v[44:47], v[144:147], v[190:193], v[44:47]
	v_mfma_f32_16x16x32_bf16 v[40:43], v[152:155], v[190:193], v[40:43]
	v_mfma_f32_16x16x32_bf16 v[28:31], v[144:147], v[198:201], v[28:31]
	v_mfma_f32_16x16x32_bf16 v[24:27], v[152:155], v[198:201], v[24:27]
	v_mfma_f32_16x16x32_bf16 v[12:15], v[144:147], v[206:209], v[12:15]
	v_mfma_f32_16x16x32_bf16 v[8:11], v[152:155], v[206:209], v[8:11]
	v_mfma_f32_16x16x32_bf16 v[60:63], v[148:151], v[186:189], v[60:63]
	v_mfma_f32_16x16x32_bf16 v[56:59], v[156:159], v[186:189], v[56:59]
	v_mfma_f32_16x16x32_bf16 v[44:47], v[148:151], v[194:197], v[44:47]
	v_mfma_f32_16x16x32_bf16 v[40:43], v[156:159], v[194:197], v[40:43]
	v_mfma_f32_16x16x32_bf16 v[28:31], v[148:151], v[202:205], v[28:31]
	v_mfma_f32_16x16x32_bf16 v[24:27], v[156:159], v[202:205], v[24:27]
	v_mfma_f32_16x16x32_bf16 v[12:15], v[148:151], v[210:213], v[12:15]
	v_mfma_f32_16x16x32_bf16 v[8:11], v[156:159], v[210:213], v[8:11]
	s_setprio 0
	s_setprio 1
	v_mfma_f32_16x16x32_bf16 v[52:55], v[160:163], v[182:185], v[52:55]
	v_mfma_f32_16x16x32_bf16 v[48:51], v[174:177], v[182:185], v[48:51]
	v_mfma_f32_16x16x32_bf16 v[36:39], v[160:163], v[190:193], v[36:39]
	v_mfma_f32_16x16x32_bf16 v[32:35], v[174:177], v[190:193], v[32:35]
	v_mfma_f32_16x16x32_bf16 v[20:23], v[160:163], v[198:201], v[20:23]
	v_mfma_f32_16x16x32_bf16 v[16:19], v[174:177], v[198:201], v[16:19]
	v_mfma_f32_16x16x32_bf16 v[4:7], v[160:163], v[206:209], v[4:7]
	v_mfma_f32_16x16x32_bf16 v[0:3], v[174:177], v[206:209], v[0:3]
	v_mfma_f32_16x16x32_bf16 v[52:55], v[164:167], v[186:189], v[52:55]
	v_mfma_f32_16x16x32_bf16 v[48:51], v[178:181], v[186:189], v[48:51]
	v_mfma_f32_16x16x32_bf16 v[36:39], v[164:167], v[194:197], v[36:39]
	v_mfma_f32_16x16x32_bf16 v[32:35], v[178:181], v[194:197], v[32:35]
	v_mfma_f32_16x16x32_bf16 v[20:23], v[164:167], v[202:205], v[20:23]
	v_mfma_f32_16x16x32_bf16 v[16:19], v[178:181], v[202:205], v[16:19]
	v_mfma_f32_16x16x32_bf16 v[4:7], v[164:167], v[210:213], v[4:7]
	v_mfma_f32_16x16x32_bf16 v[0:3], v[178:181], v[210:213], v[0:3]
	s_setprio 0
	s_barrier
	s_cbranch_scc1 .Lmy_rot11_exit
	ds_read_b128 v[144:147], v171
	ds_read_b128 v[148:151], v171 offset:1024
	ds_read_b128 v[152:155], v171 offset:2048
	ds_read_b128 v[156:159], v171 offset:3072
	ds_read_b128 v[160:163], v172
	ds_read_b128 v[164:167], v172 offset:1024
	ds_read_b128 v[174:177], v172 offset:2048
	ds_read_b128 v[178:181], v172 offset:3072
	s_branch .Lmy_rot11_head
